# v38 + GEMM loops: redundant s_waitcnt lgkmcnt(0) behind each pre-MFMA barrier removed (the same wait sits in front of the barrier)
# baseline (speedup 1.0000x reference)
; #define PG8_STAGE(bufoff, gbase, voff) do { _Pragma("unroll") for (int _i = 0; _i < 2; ++_i) \
;         __builtin_amdgcn_global_load_lds((const unsigned*)((const char*)(gbase) + (voff)[_i]), (PG8_LAS unsigned*)(lds + (bufoff) + ldsw + _i * 8192), 16, 0, 0); } while (0)
; #define PG8_LDA(dst, b, h) do { _Pragma("unroll") for (int m = 0; m < 4; ++m) _Pragma("unroll") for (int k = 0; k < 2; ++k) dst[m][k] = *(const PG8_LAS bf16x8*)(lds + PG8_SA(b, h) + aoff + m * 2048 + k * 1024); } while (0)
; #define PG8_LDB(dst, b, h) do { _Pragma("unroll") for (int n = 0; n < 2; ++n) _Pragma("unroll") for (int k = 0; k < 2; ++k) dst[n][k] = *(const PG8_LAS bf16x8*)(lds + PG8_SB(b, h) + boff + n * 2048 + k * 1024); } while (0)
; #define PG8_MMA(ai, bj, At, Bt) do { __builtin_amdgcn_s_setprio(1); _Pragma("unroll") for (int m = 0; m < 4; ++m) _Pragma("unroll") for (int n = 0; n < 2; ++n) _Pragma("unroll") for (int k = 0; k < 2; ++k) \
;         acc[ai][bj][m][n] = __builtin_amdgcn_mfma_f32_16x16x32_bf16(Bt[n][k], At[m][k], acc[ai][bj][m][n], 0, 0, 0); __builtin_amdgcn_s_setprio(0); } while (0)
; #define PG8_WAIT_V(n) asm volatile("s_waitcnt vmcnt(" #n ")" ::: "memory")
; #define PG8_BAR __builtin_amdgcn_s_barrier()
; template <class Epi, class Sched, bool ALIGN_EPI = false, bool SP2 = false>
; __device__ __forceinline__ void gemm_phase(PG8_LAS unsigned char* lds, const Gemm g, const Sched& S, const Epi& E) {
;     ...
;         for (int t = 0; t < nt; t += 2) {
;             const bool last = (t == nt - 2);
;             const char* a1 = cA + (size_t)(t + 1) * kstep;
;             const char* a2 = last ? nA : cA + (size_t)(t + 2) * kstep; const char* b2 = last ? nB : cB + (size_t)(t + 2) * kstep;
;             const char* a3 = a2 + kstep; const char* b3 = b2 + kstep;
;             if (last && has_next) S.a_ready(nxt);
;             if constexpr (SP2) {
;             PG8_LDB(B0, 0, 0); PG8_LDB(B1, 0, 1); PG8_SCHED; PG8_LDA(At, 0, 0); PG8_STAGE(PG8_SA(1, 1), a1 + hstep, voffA);
;             PG8_WAIT_V(8); PG8_WAIT_L(0); PG8_BAR; PG8_MMA(0, 0, At, B0); PG8_MMA(0, 1, At, B1); PG8_BAR; PG8_SCHED;
;             PG8_LDA(At, 0, 1); PG8_STAGE(PG8_SB(0, 0), b2, voffB); PG8_STAGE(PG8_SB(0, 1), b2 + hstep, voffB); PG8_STAGE(PG8_SA(0, 0), a2, voffA);
;             PG8_WAIT_V(8); PG8_WAIT_L(0); PG8_BAR; PG8_MMA(1, 0, At, B0); PG8_MMA(1, 1, At, B1); PG8_BAR; PG8_SCHED;
.LBB0_237:
	s_add_u32 s44, s42, 0xfffc0080
	s_addc_u32 s45, s43, -1
	s_add_i32 s63, 0, 0x10000
	s_cmp_eq_u32 s62, 12
	s_cselect_b32 s47, s13, s45
	s_cselect_b32 s46, s19, s44
	v_add_u32_e32 v141, s63, v145
	s_cselect_b32 s45, s11, s61
	s_cselect_b32 s44, s41, s60
	s_add_i32 s66, 0, 0x14000
	ds_read_b128 v[150:153], v141
	ds_read_b128 v[170:173], v141 offset:1024
	ds_read_b128 v[174:177], v141 offset:2048
	ds_read_b128 v[178:181], v141 offset:3072
	v_add_u32_e32 v141, s66, v145
	ds_read_b128 v[182:185], v141
	ds_read_b128 v[186:189], v141 offset:1024
	ds_read_b128 v[190:193], v141 offset:2048
	ds_read_b128 v[194:197], v141 offset:3072
	v_lshl_add_u64 v[154:155], s[42:43], 0, v[136:137]
	s_add_i32 m0, s49, 0xc000
	ds_read_b128 v[198:201], v149
	ds_read_b128 v[202:205], v149 offset:1024
	ds_read_b128 v[206:209], v149 offset:2048
	ds_read_b128 v[210:213], v149 offset:3072
	ds_read_b128 v[214:217], v149 offset:4096
	ds_read_b128 v[218:221], v149 offset:5120
	ds_read_b128 v[222:225], v149 offset:6144
	ds_read_b128 v[226:229], v149 offset:7168
	global_load_lds_dwordx4 v[154:155], off
	v_lshl_add_u64 v[154:155], s[42:43], 0, v[138:139]
	s_add_i32 m0, s49, 0xe000
	s_nop 0
	global_load_lds_dwordx4 v[154:155], off
	s_waitcnt vmcnt(8)
	s_waitcnt lgkmcnt(0)
	s_barrier
	v_mfma_f32_16x16x32_bf16 v[124:127], v[150:153], v[198:201], v[124:127]
	v_mfma_f32_16x16x32_bf16 v[120:123], v[174:177], v[198:201], v[120:123]
	v_mfma_f32_16x16x32_bf16 v[108:111], v[150:153], v[206:209], v[108:111]
	v_mfma_f32_16x16x32_bf16 v[104:107], v[174:177], v[206:209], v[104:107]
	v_mfma_f32_16x16x32_bf16 v[96:99], v[150:153], v[214:217], v[96:99]
	v_mfma_f32_16x16x32_bf16 v[88:91], v[174:177], v[214:217], v[88:91]
	v_mfma_f32_16x16x32_bf16 v[80:83], v[150:153], v[222:225], v[80:83]
	v_mfma_f32_16x16x32_bf16 v[72:75], v[174:177], v[222:225], v[72:75]
	v_mfma_f32_16x16x32_bf16 v[124:127], v[170:173], v[202:205], v[124:127]
	v_mfma_f32_16x16x32_bf16 v[120:123], v[178:181], v[202:205], v[120:123]
	v_mfma_f32_16x16x32_bf16 v[108:111], v[170:173], v[210:213], v[108:111]
	v_mfma_f32_16x16x32_bf16 v[104:107], v[178:181], v[210:213], v[104:107]
	v_mfma_f32_16x16x32_bf16 v[96:99], v[170:173], v[218:221], v[96:99]
	v_mfma_f32_16x16x32_bf16 v[88:91], v[178:181], v[218:221], v[88:91]
	v_mfma_f32_16x16x32_bf16 v[80:83], v[170:173], v[226:229], v[80:83]
	v_mfma_f32_16x16x32_bf16 v[72:75], v[178:181], v[226:229], v[72:75]
	v_mfma_f32_16x16x32_bf16 v[116:119], v[182:185], v[198:201], v[116:119]
	v_mfma_f32_16x16x32_bf16 v[112:115], v[190:193], v[198:201], v[112:115]
	v_mfma_f32_16x16x32_bf16 v[100:103], v[182:185], v[206:209], v[100:103]
	v_mfma_f32_16x16x32_bf16 v[92:95], v[190:193], v[206:209], v[92:95]
	v_mfma_f32_16x16x32_bf16 v[84:87], v[182:185], v[214:217], v[84:87]
	v_mfma_f32_16x16x32_bf16 v[76:79], v[190:193], v[214:217], v[76:79]
	v_mfma_f32_16x16x32_bf16 v[68:71], v[182:185], v[222:225], v[68:71]
	v_mfma_f32_16x16x32_bf16 v[64:67], v[190:193], v[222:225], v[64:67]
	v_mfma_f32_16x16x32_bf16 v[116:119], v[186:189], v[202:205], v[116:119]
	v_mfma_f32_16x16x32_bf16 v[112:115], v[194:197], v[202:205], v[112:115]
	v_mfma_f32_16x16x32_bf16 v[100:103], v[186:189], v[210:213], v[100:103]
	v_mfma_f32_16x16x32_bf16 v[92:95], v[194:197], v[210:213], v[92:95]
	v_mfma_f32_16x16x32_bf16 v[84:87], v[186:189], v[218:221], v[84:87]
	v_mfma_f32_16x16x32_bf16 v[76:79], v[194:197], v[218:221], v[76:79]
	v_mfma_f32_16x16x32_bf16 v[68:71], v[186:189], v[226:229], v[68:71]
	v_mfma_f32_16x16x32_bf16 v[64:67], v[194:197], v[226:229], v[64:67]
	s_barrier
	s_add_i32 s63, s63, s34
	v_lshl_add_u64 v[154:155], s[44:45], 0, v[132:133]
	s_mov_b32 m0, s63
	ds_read_b128 v[198:201], v149 offset:16384
	ds_read_b128 v[202:205], v149 offset:17408
	ds_read_b128 v[206:209], v149 offset:18432
	ds_read_b128 v[210:213], v149 offset:19456
	ds_read_b128 v[214:217], v149 offset:20480
	ds_read_b128 v[218:221], v149 offset:21504
	ds_read_b128 v[222:225], v149 offset:22528
	ds_read_b128 v[226:229], v149 offset:23552
	global_load_lds_dwordx4 v[154:155], off
	s_add_i32 m0, s63, 0x2000
	s_add_u32 s64, s44, 0x40000
	v_lshl_add_u64 v[236:237], s[44:45], 0, v[128:129]
	s_addc_u32 s65, s45, 0
	s_add_i32 s63, s66, s34
	global_load_lds_dwordx4 v[236:237], off
	v_lshl_add_u64 v[238:239], s[64:65], 0, v[132:133]
	s_mov_b32 m0, s63
	v_lshl_add_u64 v[240:241], s[46:47], 0, v[130:131]
	global_load_lds_dwordx4 v[238:239], off
	v_lshl_add_u64 v[238:239], s[64:65], 0, v[128:129]
	s_add_i32 m0, s63, 0x2000
	s_nop 0
	global_load_lds_dwordx4 v[238:239], off
	v_lshl_add_u64 v[238:239], s[46:47], 0, v[134:135]
	s_mov_b32 m0, s49
	s_nop 0
	global_load_lds_dwordx4 v[238:239], off
	s_mov_b32 m0, s50
	s_nop 0
	global_load_lds_dwordx4 v[240:241], off
	s_waitcnt vmcnt(8)
	s_waitcnt lgkmcnt(0)
	s_barrier
; #define PG8_STAGE(bufoff, gbase, voff) do { _Pragma("unroll") for (int _i = 0; _i < 2; ++_i) \
;         __builtin_amdgcn_global_load_lds((const unsigned*)((const char*)(gbase) + (voff)[_i]), (PG8_LAS unsigned*)(lds + (bufoff) + ldsw + _i * 8192), 16, 0, 0); } while (0)
; #define PG8_LDA(dst, b, h) do { _Pragma("unroll") for (int m = 0; m < 4; ++m) _Pragma("unroll") for (int k = 0; k < 2; ++k) dst[m][k] = *(const PG8_LAS bf16x8*)(lds + PG8_SA(b, h) + aoff + m * 2048 + k * 1024); } while (0)
; #define PG8_LDB(dst, b, h) do { _Pragma("unroll") for (int n = 0; n < 2; ++n) _Pragma("unroll") for (int k = 0; k < 2; ++k) dst[n][k] = *(const PG8_LAS bf16x8*)(lds + PG8_SB(b, h) + boff + n * 2048 + k * 1024); } while (0)
; #define PG8_MMA(ai, bj, At, Bt) do { __builtin_amdgcn_s_setprio(1); _Pragma("unroll") for (int m = 0; m < 4; ++m) _Pragma("unroll") for (int n = 0; n < 2; ++n) _Pragma("unroll") for (int k = 0; k < 2; ++k) \
;         acc[ai][bj][m][n] = __builtin_amdgcn_mfma_f32_16x16x32_bf16(Bt[n][k], At[m][k], acc[ai][bj][m][n], 0, 0, 0); __builtin_amdgcn_s_setprio(0); } while (0)
; #define PG8_WAIT_V(n) asm volatile("s_waitcnt vmcnt(" #n ")" ::: "memory")
; #define PG8_WAIT_L(n) asm volatile("s_waitcnt lgkmcnt(" #n ")" ::: "memory")
; #define PG8_BAR __builtin_amdgcn_s_barrier()
; #define PG8_SCHED __builtin_amdgcn_sched_barrier(0)
; template <class Epi, class Sched, bool ALIGN_EPI = false, bool SP2 = false>
; __device__ __forceinline__ void gemm_phase(PG8_LAS unsigned char* lds, const Gemm g, const Sched& S, const Epi& E) {
;     ...
;             PG8_WAIT_V(8); PG8_WAIT_L(0); PG8_BAR; PG8_MMA(1, 0, At, B0); PG8_MMA(1, 1, At, B1); PG8_BAR; PG8_SCHED;
;             PG8_LDB(B0, 1, 0); PG8_LDB(B1, 1, 1); PG8_SCHED; PG8_LDA(At, 1, 0); PG8_STAGE(PG8_SA(0, 1), a2 + hstep, voffA);
;             PG8_WAIT_V(8); PG8_WAIT_L(0); PG8_BAR; PG8_MMA(0, 0, At, B0); PG8_MMA(0, 1, At, B1); PG8_BAR; PG8_SCHED;
	v_mfma_f32_16x16x32_bf16 v[60:63], v[150:153], v[198:201], v[60:63]
	v_mfma_f32_16x16x32_bf16 v[56:59], v[174:177], v[198:201], v[56:59]
	v_mfma_f32_16x16x32_bf16 v[44:47], v[150:153], v[206:209], v[44:47]
	v_mfma_f32_16x16x32_bf16 v[40:43], v[174:177], v[206:209], v[40:43]
	v_mfma_f32_16x16x32_bf16 v[32:35], v[150:153], v[214:217], v[32:35]
	v_mfma_f32_16x16x32_bf16 v[24:27], v[174:177], v[214:217], v[24:27]
	v_mfma_f32_16x16x32_bf16 v[16:19], v[150:153], v[222:225], v[16:19]
	v_mfma_f32_16x16x32_bf16 v[8:11], v[174:177], v[222:225], v[8:11]
	v_mfma_f32_16x16x32_bf16 v[60:63], v[170:173], v[202:205], v[60:63]
	v_mfma_f32_16x16x32_bf16 v[56:59], v[178:181], v[202:205], v[56:59]
	v_mfma_f32_16x16x32_bf16 v[44:47], v[170:173], v[210:213], v[44:47]
	v_mfma_f32_16x16x32_bf16 v[40:43], v[178:181], v[210:213], v[40:43]
	v_mfma_f32_16x16x32_bf16 v[32:35], v[170:173], v[218:221], v[32:35]
	v_mfma_f32_16x16x32_bf16 v[24:27], v[178:181], v[218:221], v[24:27]
	v_mfma_f32_16x16x32_bf16 v[16:19], v[170:173], v[226:229], v[16:19]
	v_mfma_f32_16x16x32_bf16 v[8:11], v[178:181], v[226:229], v[8:11]
	v_mfma_f32_16x16x32_bf16 v[52:55], v[182:185], v[198:201], v[52:55]
	v_mfma_f32_16x16x32_bf16 v[48:51], v[190:193], v[198:201], v[48:51]
	v_mfma_f32_16x16x32_bf16 v[36:39], v[182:185], v[206:209], v[36:39]
	v_mfma_f32_16x16x32_bf16 v[28:31], v[190:193], v[206:209], v[28:31]
	v_mfma_f32_16x16x32_bf16 v[20:23], v[182:185], v[214:217], v[20:23]
	v_mfma_f32_16x16x32_bf16 v[12:15], v[190:193], v[214:217], v[12:15]
	v_mfma_f32_16x16x32_bf16 v[4:7], v[182:185], v[222:225], v[4:7]
	v_mfma_f32_16x16x32_bf16 v[0:3], v[190:193], v[222:225], v[0:3]
	v_mfma_f32_16x16x32_bf16 v[52:55], v[186:189], v[202:205], v[52:55]
	v_mfma_f32_16x16x32_bf16 v[48:51], v[194:197], v[202:205], v[48:51]
	v_mfma_f32_16x16x32_bf16 v[36:39], v[186:189], v[210:213], v[36:39]
	v_mfma_f32_16x16x32_bf16 v[28:31], v[194:197], v[210:213], v[28:31]
	v_mfma_f32_16x16x32_bf16 v[20:23], v[186:189], v[218:221], v[20:23]
	v_mfma_f32_16x16x32_bf16 v[12:15], v[194:197], v[218:221], v[12:15]
	v_mfma_f32_16x16x32_bf16 v[4:7], v[186:189], v[226:229], v[4:7]
	v_mfma_f32_16x16x32_bf16 v[0:3], v[194:197], v[226:229], v[0:3]
	s_barrier
	s_add_i32 s63, 0, 0x18000
	v_add_u32_e32 v141, s63, v145
	s_add_i32 s64, 0, 0x1c000
	ds_read_b128 v[150:153], v141
	ds_read_b128 v[170:173], v141 offset:1024
	ds_read_b128 v[174:177], v141 offset:2048
	ds_read_b128 v[178:181], v141 offset:3072
	v_add_u32_e32 v141, s64, v145
	ds_read_b128 v[182:185], v141
	ds_read_b128 v[186:189], v141 offset:1024
	ds_read_b128 v[190:193], v141 offset:2048
	ds_read_b128 v[194:197], v141 offset:3072
	s_add_u32 s46, s46, 0x40000
	s_addc_u32 s47, s47, 0
	s_mov_b32 m0, s51
	v_lshl_add_u64 v[242:243], s[46:47], 0, v[134:135]
	ds_read_b128 v[198:201], v149 offset:32768
	ds_read_b128 v[202:205], v149 offset:33792
	ds_read_b128 v[206:209], v149 offset:34816
	ds_read_b128 v[210:213], v149 offset:35840
	ds_read_b128 v[214:217], v149 offset:36864
	ds_read_b128 v[218:221], v149 offset:37888
	ds_read_b128 v[222:225], v149 offset:38912
	ds_read_b128 v[226:229], v149 offset:39936
	global_load_lds_dwordx4 v[242:243], off
	v_lshl_add_u64 v[242:243], s[46:47], 0, v[130:131]
	s_mov_b32 m0, s52
	s_nop 0
	global_load_lds_dwordx4 v[242:243], off
	s_waitcnt vmcnt(8)
	s_waitcnt lgkmcnt(0)
	s_barrier
	v_mfma_f32_16x16x32_bf16 v[124:127], v[150:153], v[198:201], v[124:127]
	v_mfma_f32_16x16x32_bf16 v[120:123], v[174:177], v[198:201], v[120:123]
	v_mfma_f32_16x16x32_bf16 v[108:111], v[150:153], v[206:209], v[108:111]
	v_mfma_f32_16x16x32_bf16 v[104:107], v[174:177], v[206:209], v[104:107]
	v_mfma_f32_16x16x32_bf16 v[96:99], v[150:153], v[214:217], v[96:99]
	v_mfma_f32_16x16x32_bf16 v[88:91], v[174:177], v[214:217], v[88:91]
	v_mfma_f32_16x16x32_bf16 v[80:83], v[150:153], v[222:225], v[80:83]
	v_mfma_f32_16x16x32_bf16 v[72:75], v[174:177], v[222:225], v[72:75]
	v_mfma_f32_16x16x32_bf16 v[124:127], v[170:173], v[202:205], v[124:127]
	v_mfma_f32_16x16x32_bf16 v[120:123], v[178:181], v[202:205], v[120:123]
	v_mfma_f32_16x16x32_bf16 v[108:111], v[170:173], v[210:213], v[108:111]
	v_mfma_f32_16x16x32_bf16 v[104:107], v[178:181], v[210:213], v[104:107]
	v_mfma_f32_16x16x32_bf16 v[96:99], v[170:173], v[218:221], v[96:99]
	v_mfma_f32_16x16x32_bf16 v[88:91], v[178:181], v[218:221], v[88:91]
	v_mfma_f32_16x16x32_bf16 v[80:83], v[170:173], v[226:229], v[80:83]
	v_mfma_f32_16x16x32_bf16 v[72:75], v[178:181], v[226:229], v[72:75]
	v_mfma_f32_16x16x32_bf16 v[116:119], v[182:185], v[198:201], v[116:119]
	v_mfma_f32_16x16x32_bf16 v[112:115], v[190:193], v[198:201], v[112:115]
	v_mfma_f32_16x16x32_bf16 v[100:103], v[182:185], v[206:209], v[100:103]
	v_mfma_f32_16x16x32_bf16 v[92:95], v[190:193], v[206:209], v[92:95]
	v_mfma_f32_16x16x32_bf16 v[84:87], v[182:185], v[214:217], v[84:87]
	v_mfma_f32_16x16x32_bf16 v[76:79], v[190:193], v[214:217], v[76:79]
	v_mfma_f32_16x16x32_bf16 v[68:71], v[182:185], v[222:225], v[68:71]
	v_mfma_f32_16x16x32_bf16 v[64:67], v[190:193], v[222:225], v[64:67]
	v_mfma_f32_16x16x32_bf16 v[116:119], v[186:189], v[202:205], v[116:119]
	v_mfma_f32_16x16x32_bf16 v[112:115], v[194:197], v[202:205], v[112:115]
	v_mfma_f32_16x16x32_bf16 v[100:103], v[186:189], v[210:213], v[100:103]
	v_mfma_f32_16x16x32_bf16 v[92:95], v[194:197], v[210:213], v[92:95]
	v_mfma_f32_16x16x32_bf16 v[84:87], v[186:189], v[218:221], v[84:87]
	v_mfma_f32_16x16x32_bf16 v[76:79], v[194:197], v[218:221], v[76:79]
	v_mfma_f32_16x16x32_bf16 v[68:71], v[186:189], v[226:229], v[68:71]
	v_mfma_f32_16x16x32_bf16 v[64:67], v[194:197], v[226:229], v[64:67]
	s_barrier
; #define PG8_STAGE(bufoff, gbase, voff) do { _Pragma("unroll") for (int _i = 0; _i < 2; ++_i) \
;         __builtin_amdgcn_global_load_lds((const unsigned*)((const char*)(gbase) + (voff)[_i]), (PG8_LAS unsigned*)(lds + (bufoff) + ldsw + _i * 8192), 16, 0, 0); } while (0)
; #define PG8_LDA(dst, b, h) do { _Pragma("unroll") for (int m = 0; m < 4; ++m) _Pragma("unroll") for (int k = 0; k < 2; ++k) dst[m][k] = *(const PG8_LAS bf16x8*)(lds + PG8_SA(b, h) + aoff + m * 2048 + k * 1024); } while (0)
; #define PG8_MMA(ai, bj, At, Bt) do { __builtin_amdgcn_s_setprio(1); _Pragma("unroll") for (int m = 0; m < 4; ++m) _Pragma("unroll") for (int n = 0; n < 2; ++n) _Pragma("unroll") for (int k = 0; k < 2; ++k) \
;         acc[ai][bj][m][n] = __builtin_amdgcn_mfma_f32_16x16x32_bf16(Bt[n][k], At[m][k], acc[ai][bj][m][n], 0, 0, 0); __builtin_amdgcn_s_setprio(0); } while (0)
; #define PG8_WAIT_V(n) asm volatile("s_waitcnt vmcnt(" #n ")" ::: "memory")
; #define PG8_WAIT_L(n) asm volatile("s_waitcnt lgkmcnt(" #n ")" ::: "memory")
; #define PG8_BAR __builtin_amdgcn_s_barrier()
; #define PG8_SCHED __builtin_amdgcn_sched_barrier(0)
; template <class Epi, class Sched, bool ALIGN_EPI = false, bool SP2 = false>
; __device__ __forceinline__ void gemm_phase(PG8_LAS unsigned char* lds, const Gemm g, const Sched& S, const Epi& E) {
;     ...
;         for (int t = 0; t < nt; t += 2) {
;     ...
;             PG8_LDA(At, 1, 1); PG8_STAGE(PG8_SB(1, 0), b3, voffB); PG8_STAGE(PG8_SB(1, 1), b3 + hstep, voffB); PG8_STAGE(PG8_SA(1, 0), a3, voffA);
;             PG8_WAIT_V(8); PG8_WAIT_L(0); PG8_BAR; PG8_MMA(1, 0, At, B0); PG8_MMA(1, 1, At, B1); PG8_BAR; PG8_SCHED;
;     ...
;         if constexpr (ALIGN_EPI) { if (wr == 0) PG8_BAR; }
	s_add_i32 s46, s63, s34
	v_lshl_add_u64 v[154:155], v[154:155], 0, s[96:97]
	s_mov_b32 m0, s46
	ds_read_b128 v[198:201], v149 offset:49152
	ds_read_b128 v[202:205], v149 offset:50176
	ds_read_b128 v[206:209], v149 offset:51200
	ds_read_b128 v[210:213], v149 offset:52224
	ds_read_b128 v[214:217], v149 offset:53248
	ds_read_b128 v[218:221], v149 offset:54272
	ds_read_b128 v[222:225], v149 offset:55296
	ds_read_b128 v[226:229], v149 offset:56320
	global_load_lds_dwordx4 v[154:155], off
	s_add_i32 m0, s46, 0x2000
	s_add_u32 s44, s44, 0x40080
	v_lshl_add_u64 v[154:155], v[236:237], 0, s[96:97]
	s_addc_u32 s45, s45, 0
	s_add_i32 s46, s64, s34
	global_load_lds_dwordx4 v[154:155], off
	v_lshl_add_u64 v[154:155], s[44:45], 0, v[132:133]
	s_mov_b32 m0, s46
	s_nop 0
	global_load_lds_dwordx4 v[154:155], off
	v_lshl_add_u64 v[154:155], s[44:45], 0, v[128:129]
	s_add_i32 m0, s46, 0x2000
	s_nop 0
	global_load_lds_dwordx4 v[154:155], off
	v_lshl_add_u64 v[154:155], v[238:239], 0, s[96:97]
	s_mov_b32 m0, s58
	s_nop 0
	global_load_lds_dwordx4 v[154:155], off
	v_lshl_add_u64 v[154:155], v[240:241], 0, s[96:97]
	s_mov_b32 m0, s59
	s_nop 0
	global_load_lds_dwordx4 v[154:155], off
	s_waitcnt vmcnt(8)
	s_waitcnt lgkmcnt(0)
	s_barrier
	v_mfma_f32_16x16x32_bf16 v[60:63], v[150:153], v[198:201], v[60:63]
	v_mfma_f32_16x16x32_bf16 v[56:59], v[174:177], v[198:201], v[56:59]
	v_mfma_f32_16x16x32_bf16 v[44:47], v[150:153], v[206:209], v[44:47]
	v_mfma_f32_16x16x32_bf16 v[40:43], v[174:177], v[206:209], v[40:43]
	v_mfma_f32_16x16x32_bf16 v[32:35], v[150:153], v[214:217], v[32:35]
	v_mfma_f32_16x16x32_bf16 v[24:27], v[174:177], v[214:217], v[24:27]
	v_mfma_f32_16x16x32_bf16 v[16:19], v[150:153], v[222:225], v[16:19]
	v_mfma_f32_16x16x32_bf16 v[8:11], v[174:177], v[222:225], v[8:11]
	v_mfma_f32_16x16x32_bf16 v[60:63], v[170:173], v[202:205], v[60:63]
	v_mfma_f32_16x16x32_bf16 v[56:59], v[178:181], v[202:205], v[56:59]
	v_mfma_f32_16x16x32_bf16 v[44:47], v[170:173], v[210:213], v[44:47]
	v_mfma_f32_16x16x32_bf16 v[40:43], v[178:181], v[210:213], v[40:43]
	v_mfma_f32_16x16x32_bf16 v[32:35], v[170:173], v[218:221], v[32:35]
	v_mfma_f32_16x16x32_bf16 v[24:27], v[178:181], v[218:221], v[24:27]
	v_mfma_f32_16x16x32_bf16 v[16:19], v[170:173], v[226:229], v[16:19]
	v_mfma_f32_16x16x32_bf16 v[8:11], v[178:181], v[226:229], v[8:11]
	v_mfma_f32_16x16x32_bf16 v[52:55], v[182:185], v[198:201], v[52:55]
	v_mfma_f32_16x16x32_bf16 v[48:51], v[190:193], v[198:201], v[48:51]
	v_mfma_f32_16x16x32_bf16 v[36:39], v[182:185], v[206:209], v[36:39]
	v_mfma_f32_16x16x32_bf16 v[28:31], v[190:193], v[206:209], v[28:31]
	v_mfma_f32_16x16x32_bf16 v[20:23], v[182:185], v[214:217], v[20:23]
	v_mfma_f32_16x16x32_bf16 v[12:15], v[190:193], v[214:217], v[12:15]
	v_mfma_f32_16x16x32_bf16 v[4:7], v[182:185], v[222:225], v[4:7]
	v_mfma_f32_16x16x32_bf16 v[0:3], v[190:193], v[222:225], v[0:3]
	v_mfma_f32_16x16x32_bf16 v[52:55], v[186:189], v[202:205], v[52:55]
	v_mfma_f32_16x16x32_bf16 v[48:51], v[194:197], v[202:205], v[48:51]
	v_mfma_f32_16x16x32_bf16 v[36:39], v[186:189], v[210:213], v[36:39]
	v_mfma_f32_16x16x32_bf16 v[28:31], v[194:197], v[210:213], v[28:31]
	v_mfma_f32_16x16x32_bf16 v[20:23], v[186:189], v[218:221], v[20:23]
	v_mfma_f32_16x16x32_bf16 v[12:15], v[194:197], v[218:221], v[12:15]
	v_mfma_f32_16x16x32_bf16 v[4:7], v[186:189], v[226:229], v[4:7]
	v_mfma_f32_16x16x32_bf16 v[0:3], v[194:197], v[226:229], v[0:3]
	s_barrier
	s_add_i32 s62, s62, 2
	s_add_u32 s42, s42, 0x100
	s_addc_u32 s43, s43, 0
	s_add_u32 s60, s60, 0x100
	s_addc_u32 s61, s61, 0
	s_cmp_gt_u32 s62, 13
	s_cbranch_scc0 .LBB0_237
	s_and_b64 vcc, exec, s[8:9]
	s_cbranch_vccz .LBB0_240
	s_barrier

; #define PG8_STAGE(bufoff, gbase, voff) do { _Pragma("unroll") for (int _i = 0; _i < 2; ++_i) \
;         __builtin_amdgcn_global_load_lds((const unsigned*)((const char*)(gbase) + (voff)[_i]), (PG8_LAS unsigned*)(lds + (bufoff) + ldsw + _i * 8192), 16, 0, 0); } while (0)
; #define PG8_LDA(dst, b, h) do { _Pragma("unroll") for (int m = 0; m < 4; ++m) _Pragma("unroll") for (int k = 0; k < 2; ++k) dst[m][k] = *(const PG8_LAS bf16x8*)(lds + PG8_SA(b, h) + aoff + m * 2048 + k * 1024); } while (0)
; #define PG8_LDB(dst, b, h) do { _Pragma("unroll") for (int n = 0; n < 2; ++n) _Pragma("unroll") for (int k = 0; k < 2; ++k) dst[n][k] = *(const PG8_LAS bf16x8*)(lds + PG8_SB(b, h) + boff + n * 2048 + k * 1024); } while (0)
; #define PG8_MMA(ai, bj, At, Bt) do { __builtin_amdgcn_s_setprio(1); _Pragma("unroll") for (int m = 0; m < 4; ++m) _Pragma("unroll") for (int n = 0; n < 2; ++n) _Pragma("unroll") for (int k = 0; k < 2; ++k) \
;         acc[ai][bj][m][n] = __builtin_amdgcn_mfma_f32_16x16x32_bf16(Bt[n][k], At[m][k], acc[ai][bj][m][n], 0, 0, 0); __builtin_amdgcn_s_setprio(0); } while (0)
; #define PG8_WAIT_V(n) asm volatile("s_waitcnt vmcnt(" #n ")" ::: "memory")
; #define PG8_BAR __builtin_amdgcn_s_barrier()
; template <class Epi, class Sched, bool ALIGN_EPI = false, bool SP2 = false>
; __device__ __forceinline__ void gemm_phase(PG8_LAS unsigned char* lds, const Gemm g, const Sched& S, const Epi& E) {
;     ...
;         for (int t = 0; t < nt; t += 2) {
;             const bool last = (t == nt - 2);
;             const char* a1 = cA + (size_t)(t + 1) * kstep;
;             const char* a2 = last ? nA : cA + (size_t)(t + 2) * kstep; const char* b2 = last ? nB : cB + (size_t)(t + 2) * kstep;
;             const char* a3 = a2 + kstep; const char* b3 = b2 + kstep;
;             if (last && has_next) S.a_ready(nxt);
;             if constexpr (SP2) {
;             PG8_LDB(B0, 0, 0); PG8_LDB(B1, 0, 1); PG8_SCHED; PG8_LDA(At, 0, 0); PG8_STAGE(PG8_SA(1, 1), a1 + hstep, voffA);
;             PG8_WAIT_V(8); PG8_WAIT_L(0); PG8_BAR; PG8_MMA(0, 0, At, B0); PG8_MMA(0, 1, At, B1); PG8_BAR; PG8_SCHED;
;             PG8_LDA(At, 0, 1); PG8_STAGE(PG8_SB(0, 0), b2, voffB); PG8_STAGE(PG8_SB(0, 1), b2 + hstep, voffB); PG8_STAGE(PG8_SA(0, 0), a2, voffA);
;             PG8_WAIT_V(8); PG8_WAIT_L(0); PG8_BAR; PG8_MMA(1, 0, At, B0); PG8_MMA(1, 1, At, B1); PG8_BAR; PG8_SCHED;
.LBB0_264:
	s_add_u32 s12, s10, 0x100
	s_addc_u32 s13, s11, 0
	s_add_i32 s34, 0, 0x10000
	s_cmp_eq_u32 s31, 40
	s_cselect_b32 s17, s7, s13
	s_cselect_b32 s16, s6, s12
	s_cselect_b32 s15, s9, s30
	s_cselect_b32 s14, s8, s29
	s_add_i32 s35, 0, 0x14000
	v_add_u32_e32 v132, s34, v169
	v_add_u32_e32 v180, s35, v169
	ds_read_b128 v[104:107], v132
	ds_read_b128 v[120:123], v132 offset:1024
	ds_read_b128 v[128:131], v132 offset:2048
	ds_read_b128 v[132:135], v132 offset:3072
	ds_read_b128 v[136:139], v180
	ds_read_b128 v[148:151], v180 offset:1024
	ds_read_b128 v[152:155], v180 offset:2048
	ds_read_b128 v[180:183], v180 offset:3072
	v_lshl_add_u64 v[216:217], s[10:11], 0, v[176:177]
	s_add_i32 m0, s21, 0xc000
	ds_read_b128 v[184:187], v239
	ds_read_b128 v[188:191], v239 offset:1024
	ds_read_b128 v[192:195], v239 offset:2048
	ds_read_b128 v[196:199], v239 offset:3072
	ds_read_b128 v[200:203], v239 offset:4096
	ds_read_b128 v[204:207], v239 offset:5120
	ds_read_b128 v[208:211], v239 offset:6144
	ds_read_b128 v[212:215], v239 offset:7168
	global_load_lds_dwordx4 v[216:217], off
	v_lshl_add_u64 v[216:217], s[10:11], 0, v[178:179]
	s_add_i32 m0, s21, 0xe000
	s_nop 0
	global_load_lds_dwordx4 v[216:217], off
	s_waitcnt vmcnt(8)
	s_waitcnt lgkmcnt(0)
	s_barrier
	v_mfma_f32_16x16x32_bf16 v[144:147], v[104:107], v[184:187], v[144:147]
	v_mfma_f32_16x16x32_bf16 v[140:143], v[128:131], v[184:187], v[140:143]
	v_mfma_f32_16x16x32_bf16 v[112:115], v[104:107], v[192:195], v[112:115]
	v_mfma_f32_16x16x32_bf16 v[108:111], v[128:131], v[192:195], v[108:111]
	v_mfma_f32_16x16x32_bf16 v[92:95], v[104:107], v[200:203], v[92:95]
	v_mfma_f32_16x16x32_bf16 v[88:91], v[128:131], v[200:203], v[88:91]
	v_mfma_f32_16x16x32_bf16 v[76:79], v[104:107], v[208:211], v[76:79]
	v_mfma_f32_16x16x32_bf16 v[72:75], v[128:131], v[208:211], v[72:75]
	v_mfma_f32_16x16x32_bf16 v[144:147], v[120:123], v[188:191], v[144:147]
	v_mfma_f32_16x16x32_bf16 v[140:143], v[132:135], v[188:191], v[140:143]
	v_mfma_f32_16x16x32_bf16 v[112:115], v[120:123], v[196:199], v[112:115]
	v_mfma_f32_16x16x32_bf16 v[108:111], v[132:135], v[196:199], v[108:111]
	v_mfma_f32_16x16x32_bf16 v[92:95], v[120:123], v[204:207], v[92:95]
	v_mfma_f32_16x16x32_bf16 v[88:91], v[132:135], v[204:207], v[88:91]
	v_mfma_f32_16x16x32_bf16 v[76:79], v[120:123], v[212:215], v[76:79]
	v_mfma_f32_16x16x32_bf16 v[72:75], v[132:135], v[212:215], v[72:75]
	v_mfma_f32_16x16x32_bf16 v[124:127], v[136:139], v[184:187], v[124:127]
	v_mfma_f32_16x16x32_bf16 v[116:119], v[152:155], v[184:187], v[116:119]
	v_mfma_f32_16x16x32_bf16 v[100:103], v[136:139], v[192:195], v[100:103]
	v_mfma_f32_16x16x32_bf16 v[96:99], v[152:155], v[192:195], v[96:99]
	v_mfma_f32_16x16x32_bf16 v[84:87], v[136:139], v[200:203], v[84:87]
	v_mfma_f32_16x16x32_bf16 v[80:83], v[152:155], v[200:203], v[80:83]
	v_mfma_f32_16x16x32_bf16 v[68:71], v[136:139], v[208:211], v[68:71]
	v_mfma_f32_16x16x32_bf16 v[64:67], v[152:155], v[208:211], v[64:67]
	v_mfma_f32_16x16x32_bf16 v[124:127], v[148:151], v[188:191], v[124:127]
	v_mfma_f32_16x16x32_bf16 v[116:119], v[180:183], v[188:191], v[116:119]
	v_mfma_f32_16x16x32_bf16 v[100:103], v[148:151], v[196:199], v[100:103]
	v_mfma_f32_16x16x32_bf16 v[96:99], v[180:183], v[196:199], v[96:99]
	v_mfma_f32_16x16x32_bf16 v[84:87], v[148:151], v[204:207], v[84:87]
	v_mfma_f32_16x16x32_bf16 v[80:83], v[180:183], v[204:207], v[80:83]
	v_mfma_f32_16x16x32_bf16 v[68:71], v[148:151], v[212:215], v[68:71]
	v_mfma_f32_16x16x32_bf16 v[64:67], v[180:183], v[212:215], v[64:67]
	s_barrier
	s_add_i32 s10, s34, s20
	v_lshl_add_u64 v[216:217], s[14:15], 0, v[156:157]
	s_mov_b32 m0, s10
	ds_read_b128 v[184:187], v239 offset:16384
	ds_read_b128 v[188:191], v239 offset:17408
	ds_read_b128 v[192:195], v239 offset:18432
	ds_read_b128 v[196:199], v239 offset:19456
	ds_read_b128 v[200:203], v239 offset:20480
	ds_read_b128 v[204:207], v239 offset:21504
	ds_read_b128 v[208:211], v239 offset:22528
	ds_read_b128 v[212:215], v239 offset:23552
	global_load_lds_dwordx4 v[216:217], off
	s_add_i32 m0, s10, 0x2000
	s_add_u32 s10, s14, 0xb0000
	v_lshl_add_u64 v[218:219], s[14:15], 0, v[170:171]
	s_addc_u32 s11, s15, 0
	s_add_i32 s34, s35, s20
	global_load_lds_dwordx4 v[218:219], off
	v_lshl_add_u64 v[220:221], s[10:11], 0, v[156:157]
	s_mov_b32 m0, s34
	v_lshl_add_u64 v[222:223], s[16:17], 0, v[172:173]
	global_load_lds_dwordx4 v[220:221], off
	v_lshl_add_u64 v[220:221], s[10:11], 0, v[170:171]
	s_add_i32 m0, s34, 0x2000
	s_nop 0
	global_load_lds_dwordx4 v[220:221], off
	v_lshl_add_u64 v[220:221], s[16:17], 0, v[174:175]
	s_mov_b32 m0, s21
	s_nop 0
	global_load_lds_dwordx4 v[220:221], off
	s_mov_b32 m0, s27
	s_nop 0
	global_load_lds_dwordx4 v[222:223], off
	s_waitcnt vmcnt(8)
	s_waitcnt lgkmcnt(0)
	s_barrier
; #define PG8_STAGE(bufoff, gbase, voff) do { _Pragma("unroll") for (int _i = 0; _i < 2; ++_i) \
;         __builtin_amdgcn_global_load_lds((const unsigned*)((const char*)(gbase) + (voff)[_i]), (PG8_LAS unsigned*)(lds + (bufoff) + ldsw + _i * 8192), 16, 0, 0); } while (0)
; #define PG8_LDA(dst, b, h) do { _Pragma("unroll") for (int m = 0; m < 4; ++m) _Pragma("unroll") for (int k = 0; k < 2; ++k) dst[m][k] = *(const PG8_LAS bf16x8*)(lds + PG8_SA(b, h) + aoff + m * 2048 + k * 1024); } while (0)
; #define PG8_LDB(dst, b, h) do { _Pragma("unroll") for (int n = 0; n < 2; ++n) _Pragma("unroll") for (int k = 0; k < 2; ++k) dst[n][k] = *(const PG8_LAS bf16x8*)(lds + PG8_SB(b, h) + boff + n * 2048 + k * 1024); } while (0)
; #define PG8_MMA(ai, bj, At, Bt) do { __builtin_amdgcn_s_setprio(1); _Pragma("unroll") for (int m = 0; m < 4; ++m) _Pragma("unroll") for (int n = 0; n < 2; ++n) _Pragma("unroll") for (int k = 0; k < 2; ++k) \
;         acc[ai][bj][m][n] = __builtin_amdgcn_mfma_f32_16x16x32_bf16(Bt[n][k], At[m][k], acc[ai][bj][m][n], 0, 0, 0); __builtin_amdgcn_s_setprio(0); } while (0)
; #define PG8_WAIT_V(n) asm volatile("s_waitcnt vmcnt(" #n ")" ::: "memory")
; #define PG8_WAIT_L(n) asm volatile("s_waitcnt lgkmcnt(" #n ")" ::: "memory")
; #define PG8_BAR __builtin_amdgcn_s_barrier()
; #define PG8_SCHED __builtin_amdgcn_sched_barrier(0)
; template <class Epi, class Sched, bool ALIGN_EPI = false, bool SP2 = false>
; __device__ __forceinline__ void gemm_phase(PG8_LAS unsigned char* lds, const Gemm g, const Sched& S, const Epi& E) {
;     ...
;             PG8_WAIT_V(8); PG8_WAIT_L(0); PG8_BAR; PG8_MMA(1, 0, At, B0); PG8_MMA(1, 1, At, B1); PG8_BAR; PG8_SCHED;
;             PG8_LDB(B0, 1, 0); PG8_LDB(B1, 1, 1); PG8_SCHED; PG8_LDA(At, 1, 0); PG8_STAGE(PG8_SA(0, 1), a2 + hstep, voffA);
;             PG8_WAIT_V(8); PG8_WAIT_L(0); PG8_BAR; PG8_MMA(0, 0, At, B0); PG8_MMA(0, 1, At, B1); PG8_BAR; PG8_SCHED;
	v_mfma_f32_16x16x32_bf16 v[60:63], v[104:107], v[184:187], v[60:63]
	v_mfma_f32_16x16x32_bf16 v[56:59], v[128:131], v[184:187], v[56:59]
	v_mfma_f32_16x16x32_bf16 v[44:47], v[104:107], v[192:195], v[44:47]
	v_mfma_f32_16x16x32_bf16 v[40:43], v[128:131], v[192:195], v[40:43]
	v_mfma_f32_16x16x32_bf16 v[28:31], v[104:107], v[200:203], v[28:31]
	v_mfma_f32_16x16x32_bf16 v[24:27], v[128:131], v[200:203], v[24:27]
	v_mfma_f32_16x16x32_bf16 v[12:15], v[104:107], v[208:211], v[12:15]
	v_mfma_f32_16x16x32_bf16 v[8:11], v[128:131], v[208:211], v[8:11]
	v_mfma_f32_16x16x32_bf16 v[60:63], v[120:123], v[188:191], v[60:63]
	v_mfma_f32_16x16x32_bf16 v[56:59], v[132:135], v[188:191], v[56:59]
	v_mfma_f32_16x16x32_bf16 v[44:47], v[120:123], v[196:199], v[44:47]
	v_mfma_f32_16x16x32_bf16 v[40:43], v[132:135], v[196:199], v[40:43]
	v_mfma_f32_16x16x32_bf16 v[28:31], v[120:123], v[204:207], v[28:31]
	v_mfma_f32_16x16x32_bf16 v[24:27], v[132:135], v[204:207], v[24:27]
	v_mfma_f32_16x16x32_bf16 v[12:15], v[120:123], v[212:215], v[12:15]
	v_mfma_f32_16x16x32_bf16 v[8:11], v[132:135], v[212:215], v[8:11]
	v_mfma_f32_16x16x32_bf16 v[52:55], v[136:139], v[184:187], v[52:55]
	v_mfma_f32_16x16x32_bf16 v[48:51], v[152:155], v[184:187], v[48:51]
	v_mfma_f32_16x16x32_bf16 v[36:39], v[136:139], v[192:195], v[36:39]
	v_mfma_f32_16x16x32_bf16 v[32:35], v[152:155], v[192:195], v[32:35]
	v_mfma_f32_16x16x32_bf16 v[20:23], v[136:139], v[200:203], v[20:23]
	v_mfma_f32_16x16x32_bf16 v[16:19], v[152:155], v[200:203], v[16:19]
	v_mfma_f32_16x16x32_bf16 v[4:7], v[136:139], v[208:211], v[4:7]
	v_mfma_f32_16x16x32_bf16 v[0:3], v[152:155], v[208:211], v[0:3]
	v_mfma_f32_16x16x32_bf16 v[52:55], v[148:151], v[188:191], v[52:55]
	v_mfma_f32_16x16x32_bf16 v[48:51], v[180:183], v[188:191], v[48:51]
	v_mfma_f32_16x16x32_bf16 v[36:39], v[148:151], v[196:199], v[36:39]
	v_mfma_f32_16x16x32_bf16 v[32:35], v[180:183], v[196:199], v[32:35]
	v_mfma_f32_16x16x32_bf16 v[20:23], v[148:151], v[204:207], v[20:23]
	v_mfma_f32_16x16x32_bf16 v[16:19], v[180:183], v[204:207], v[16:19]
	v_mfma_f32_16x16x32_bf16 v[4:7], v[148:151], v[212:215], v[4:7]
	v_mfma_f32_16x16x32_bf16 v[0:3], v[180:183], v[212:215], v[0:3]
	s_barrier
	s_add_i32 s34, 0, 0x18000
	s_add_i32 s35, 0, 0x1c000
	v_add_u32_e32 v132, s34, v169
	v_add_u32_e32 v180, s35, v169
	ds_read_b128 v[104:107], v132
	ds_read_b128 v[120:123], v132 offset:1024
	ds_read_b128 v[128:131], v132 offset:2048
	ds_read_b128 v[132:135], v132 offset:3072
	ds_read_b128 v[136:139], v180
	ds_read_b128 v[148:151], v180 offset:1024
	ds_read_b128 v[152:155], v180 offset:2048
	ds_read_b128 v[180:183], v180 offset:3072
	s_add_u32 s10, s16, 0xb0000
	s_addc_u32 s11, s17, 0
	s_mov_b32 m0, s54
	v_lshl_add_u64 v[224:225], s[10:11], 0, v[174:175]
	ds_read_b128 v[184:187], v239 offset:32768
	ds_read_b128 v[188:191], v239 offset:33792
	ds_read_b128 v[192:195], v239 offset:34816
	ds_read_b128 v[196:199], v239 offset:35840
	ds_read_b128 v[200:203], v239 offset:36864
	ds_read_b128 v[204:207], v239 offset:37888
	ds_read_b128 v[208:211], v239 offset:38912
	ds_read_b128 v[212:215], v239 offset:39936
	global_load_lds_dwordx4 v[224:225], off
	v_lshl_add_u64 v[224:225], s[10:11], 0, v[172:173]
	s_mov_b32 m0, s55
	s_nop 0
	global_load_lds_dwordx4 v[224:225], off
	s_waitcnt vmcnt(8)
	s_waitcnt lgkmcnt(0)
	s_barrier
	v_mfma_f32_16x16x32_bf16 v[144:147], v[104:107], v[184:187], v[144:147]
	v_mfma_f32_16x16x32_bf16 v[140:143], v[128:131], v[184:187], v[140:143]
	v_mfma_f32_16x16x32_bf16 v[112:115], v[104:107], v[192:195], v[112:115]
	v_mfma_f32_16x16x32_bf16 v[108:111], v[128:131], v[192:195], v[108:111]
	v_mfma_f32_16x16x32_bf16 v[92:95], v[104:107], v[200:203], v[92:95]
	v_mfma_f32_16x16x32_bf16 v[88:91], v[128:131], v[200:203], v[88:91]
	v_mfma_f32_16x16x32_bf16 v[76:79], v[104:107], v[208:211], v[76:79]
	v_mfma_f32_16x16x32_bf16 v[72:75], v[128:131], v[208:211], v[72:75]
	v_mfma_f32_16x16x32_bf16 v[144:147], v[120:123], v[188:191], v[144:147]
	v_mfma_f32_16x16x32_bf16 v[140:143], v[132:135], v[188:191], v[140:143]
	v_mfma_f32_16x16x32_bf16 v[112:115], v[120:123], v[196:199], v[112:115]
	v_mfma_f32_16x16x32_bf16 v[108:111], v[132:135], v[196:199], v[108:111]
	v_mfma_f32_16x16x32_bf16 v[92:95], v[120:123], v[204:207], v[92:95]
	v_mfma_f32_16x16x32_bf16 v[88:91], v[132:135], v[204:207], v[88:91]
	v_mfma_f32_16x16x32_bf16 v[76:79], v[120:123], v[212:215], v[76:79]
	v_mfma_f32_16x16x32_bf16 v[72:75], v[132:135], v[212:215], v[72:75]
	v_mfma_f32_16x16x32_bf16 v[124:127], v[136:139], v[184:187], v[124:127]
	v_mfma_f32_16x16x32_bf16 v[116:119], v[152:155], v[184:187], v[116:119]
	v_mfma_f32_16x16x32_bf16 v[100:103], v[136:139], v[192:195], v[100:103]
	v_mfma_f32_16x16x32_bf16 v[96:99], v[152:155], v[192:195], v[96:99]
	v_mfma_f32_16x16x32_bf16 v[84:87], v[136:139], v[200:203], v[84:87]
	v_mfma_f32_16x16x32_bf16 v[80:83], v[152:155], v[200:203], v[80:83]
	v_mfma_f32_16x16x32_bf16 v[68:71], v[136:139], v[208:211], v[68:71]
	v_mfma_f32_16x16x32_bf16 v[64:67], v[152:155], v[208:211], v[64:67]
	v_mfma_f32_16x16x32_bf16 v[124:127], v[148:151], v[188:191], v[124:127]
	v_mfma_f32_16x16x32_bf16 v[116:119], v[180:183], v[188:191], v[116:119]
	v_mfma_f32_16x16x32_bf16 v[100:103], v[148:151], v[196:199], v[100:103]
	v_mfma_f32_16x16x32_bf16 v[96:99], v[180:183], v[196:199], v[96:99]
	v_mfma_f32_16x16x32_bf16 v[84:87], v[148:151], v[204:207], v[84:87]
	v_mfma_f32_16x16x32_bf16 v[80:83], v[180:183], v[204:207], v[80:83]
	v_mfma_f32_16x16x32_bf16 v[68:71], v[148:151], v[212:215], v[68:71]
	v_mfma_f32_16x16x32_bf16 v[64:67], v[180:183], v[212:215], v[64:67]
	s_barrier
; #define PG8_STAGE(bufoff, gbase, voff) do { _Pragma("unroll") for (int _i = 0; _i < 2; ++_i) \
;         __builtin_amdgcn_global_load_lds((const unsigned*)((const char*)(gbase) + (voff)[_i]), (PG8_LAS unsigned*)(lds + (bufoff) + ldsw + _i * 8192), 16, 0, 0); } while (0)
; #define PG8_LDA(dst, b, h) do { _Pragma("unroll") for (int m = 0; m < 4; ++m) _Pragma("unroll") for (int k = 0; k < 2; ++k) dst[m][k] = *(const PG8_LAS bf16x8*)(lds + PG8_SA(b, h) + aoff + m * 2048 + k * 1024); } while (0)
; #define PG8_MMA(ai, bj, At, Bt) do { __builtin_amdgcn_s_setprio(1); _Pragma("unroll") for (int m = 0; m < 4; ++m) _Pragma("unroll") for (int n = 0; n < 2; ++n) _Pragma("unroll") for (int k = 0; k < 2; ++k) \
;         acc[ai][bj][m][n] = __builtin_amdgcn_mfma_f32_16x16x32_bf16(Bt[n][k], At[m][k], acc[ai][bj][m][n], 0, 0, 0); __builtin_amdgcn_s_setprio(0); } while (0)
; #define PG8_WAIT_V(n) asm volatile("s_waitcnt vmcnt(" #n ")" ::: "memory")
; #define PG8_WAIT_L(n) asm volatile("s_waitcnt lgkmcnt(" #n ")" ::: "memory")
; #define PG8_BAR __builtin_amdgcn_s_barrier()
; #define PG8_SCHED __builtin_amdgcn_sched_barrier(0)
; template <class Epi, class Sched, bool ALIGN_EPI = false, bool SP2 = false>
; __device__ __forceinline__ void gemm_phase(PG8_LAS unsigned char* lds, const Gemm g, const Sched& S, const Epi& E) {
;     ...
;         for (int t = 0; t < nt; t += 2) {
;     ...
;             PG8_LDA(At, 1, 1); PG8_STAGE(PG8_SB(1, 0), b3, voffB); PG8_STAGE(PG8_SB(1, 1), b3 + hstep, voffB); PG8_STAGE(PG8_SA(1, 0), a3, voffA);
;             PG8_WAIT_V(8); PG8_WAIT_L(0); PG8_BAR; PG8_MMA(1, 0, At, B0); PG8_MMA(1, 1, At, B1); PG8_BAR; PG8_SCHED;
;     ...
;         if constexpr (ALIGN_EPI) { if (wr == 0) PG8_BAR; }
	s_add_i32 s10, s34, s20
	v_lshl_add_u64 v[216:217], v[216:217], 0, s[96:97]
	s_mov_b32 m0, s10
	ds_read_b128 v[184:187], v239 offset:49152
	ds_read_b128 v[188:191], v239 offset:50176
	ds_read_b128 v[192:195], v239 offset:51200
	ds_read_b128 v[196:199], v239 offset:52224
	ds_read_b128 v[200:203], v239 offset:53248
	ds_read_b128 v[204:207], v239 offset:54272
	ds_read_b128 v[208:211], v239 offset:55296
	ds_read_b128 v[212:215], v239 offset:56320
	global_load_lds_dwordx4 v[216:217], off
	s_add_i32 m0, s10, 0x2000
	s_add_u32 s10, s14, 0xb0080
	v_lshl_add_u64 v[216:217], v[218:219], 0, s[96:97]
	s_addc_u32 s11, s15, 0
	s_add_i32 s14, s35, s20
	global_load_lds_dwordx4 v[216:217], off
	v_lshl_add_u64 v[216:217], s[10:11], 0, v[156:157]
	s_mov_b32 m0, s14
	s_nop 0
	global_load_lds_dwordx4 v[216:217], off
	v_lshl_add_u64 v[216:217], s[10:11], 0, v[170:171]
	s_add_i32 m0, s14, 0x2000
	s_nop 0
	global_load_lds_dwordx4 v[216:217], off
	v_lshl_add_u64 v[216:217], v[220:221], 0, s[96:97]
	s_mov_b32 m0, s57
	s_nop 0
	global_load_lds_dwordx4 v[216:217], off
	v_lshl_add_u64 v[216:217], v[222:223], 0, s[96:97]
	s_mov_b32 m0, s58
	s_nop 0
	global_load_lds_dwordx4 v[216:217], off
	s_waitcnt vmcnt(8)
	s_waitcnt lgkmcnt(0)
	s_barrier
	v_mfma_f32_16x16x32_bf16 v[60:63], v[104:107], v[184:187], v[60:63]
	v_mfma_f32_16x16x32_bf16 v[56:59], v[128:131], v[184:187], v[56:59]
	v_mfma_f32_16x16x32_bf16 v[44:47], v[104:107], v[192:195], v[44:47]
	v_mfma_f32_16x16x32_bf16 v[40:43], v[128:131], v[192:195], v[40:43]
	v_mfma_f32_16x16x32_bf16 v[28:31], v[104:107], v[200:203], v[28:31]
	v_mfma_f32_16x16x32_bf16 v[24:27], v[128:131], v[200:203], v[24:27]
	v_mfma_f32_16x16x32_bf16 v[12:15], v[104:107], v[208:211], v[12:15]
	v_mfma_f32_16x16x32_bf16 v[8:11], v[128:131], v[208:211], v[8:11]
	v_mfma_f32_16x16x32_bf16 v[60:63], v[120:123], v[188:191], v[60:63]
	v_mfma_f32_16x16x32_bf16 v[56:59], v[132:135], v[188:191], v[56:59]
	v_mfma_f32_16x16x32_bf16 v[44:47], v[120:123], v[196:199], v[44:47]
	v_mfma_f32_16x16x32_bf16 v[40:43], v[132:135], v[196:199], v[40:43]
	v_mfma_f32_16x16x32_bf16 v[28:31], v[120:123], v[204:207], v[28:31]
	v_mfma_f32_16x16x32_bf16 v[24:27], v[132:135], v[204:207], v[24:27]
	v_mfma_f32_16x16x32_bf16 v[12:15], v[120:123], v[212:215], v[12:15]
	v_mfma_f32_16x16x32_bf16 v[8:11], v[132:135], v[212:215], v[8:11]
	v_mfma_f32_16x16x32_bf16 v[52:55], v[136:139], v[184:187], v[52:55]
	v_mfma_f32_16x16x32_bf16 v[48:51], v[152:155], v[184:187], v[48:51]
	v_mfma_f32_16x16x32_bf16 v[36:39], v[136:139], v[192:195], v[36:39]
	v_mfma_f32_16x16x32_bf16 v[32:35], v[152:155], v[192:195], v[32:35]
	v_mfma_f32_16x16x32_bf16 v[20:23], v[136:139], v[200:203], v[20:23]
	v_mfma_f32_16x16x32_bf16 v[16:19], v[152:155], v[200:203], v[16:19]
	v_mfma_f32_16x16x32_bf16 v[4:7], v[136:139], v[208:211], v[4:7]
	v_mfma_f32_16x16x32_bf16 v[0:3], v[152:155], v[208:211], v[0:3]
	v_mfma_f32_16x16x32_bf16 v[52:55], v[148:151], v[188:191], v[52:55]
	v_mfma_f32_16x16x32_bf16 v[48:51], v[180:183], v[188:191], v[48:51]
	v_mfma_f32_16x16x32_bf16 v[36:39], v[148:151], v[196:199], v[36:39]
	v_mfma_f32_16x16x32_bf16 v[32:35], v[180:183], v[196:199], v[32:35]
	v_mfma_f32_16x16x32_bf16 v[20:23], v[148:151], v[204:207], v[20:23]
	v_mfma_f32_16x16x32_bf16 v[16:19], v[180:183], v[204:207], v[16:19]
	v_mfma_f32_16x16x32_bf16 v[4:7], v[148:151], v[212:215], v[4:7]
	v_mfma_f32_16x16x32_bf16 v[0:3], v[180:183], v[212:215], v[0:3]
	s_barrier
	s_add_i32 s31, s31, 2
	s_add_u32 s29, s29, 0x100
	s_addc_u32 s30, s30, 0
	s_cmp_gt_u32 s31, 41
	s_mov_b64 s[10:11], s[12:13]
	s_cbranch_scc0 .LBB0_264
	s_and_b64 vcc, exec, s[52:53]
	s_cbranch_vccz .LBB0_267
	s_barrier

; #define PG8_STAGE(bufoff, gbase, voff) do { _Pragma("unroll") for (int _i = 0; _i < 2; ++_i) \
;         __builtin_amdgcn_global_load_lds((const unsigned*)((const char*)(gbase) + (voff)[_i]), (PG8_LAS unsigned*)(lds + (bufoff) + ldsw + _i * 8192), 16, 0, 0); } while (0)
; #define PG8_LDA(dst, b, h) do { _Pragma("unroll") for (int m = 0; m < 4; ++m) _Pragma("unroll") for (int k = 0; k < 2; ++k) dst[m][k] = *(const PG8_LAS bf16x8*)(lds + PG8_SA(b, h) + aoff + m * 2048 + k * 1024); } while (0)
; #define PG8_LDB(dst, b, h) do { _Pragma("unroll") for (int n = 0; n < 2; ++n) _Pragma("unroll") for (int k = 0; k < 2; ++k) dst[n][k] = *(const PG8_LAS bf16x8*)(lds + PG8_SB(b, h) + boff + n * 2048 + k * 1024); } while (0)
; #define PG8_MMA(ai, bj, At, Bt) do { __builtin_amdgcn_s_setprio(1); _Pragma("unroll") for (int m = 0; m < 4; ++m) _Pragma("unroll") for (int n = 0; n < 2; ++n) _Pragma("unroll") for (int k = 0; k < 2; ++k) \
;         acc[ai][bj][m][n] = __builtin_amdgcn_mfma_f32_16x16x32_bf16(Bt[n][k], At[m][k], acc[ai][bj][m][n], 0, 0, 0); __builtin_amdgcn_s_setprio(0); } while (0)
; #define PG8_WAIT_V(n) asm volatile("s_waitcnt vmcnt(" #n ")" ::: "memory")
; #define PG8_BAR __builtin_amdgcn_s_barrier()
; template <class Epi, class Sched, bool ALIGN_EPI = false, bool SP2 = false>
; __device__ __forceinline__ void gemm_phase(PG8_LAS unsigned char* lds, const Gemm g, const Sched& S, const Epi& E) {
;     ...
;         for (int t = 0; t < nt; t += 2) {
;             const bool last = (t == nt - 2);
;             const char* a1 = cA + (size_t)(t + 1) * kstep;
;             const char* a2 = last ? nA : cA + (size_t)(t + 2) * kstep; const char* b2 = last ? nB : cB + (size_t)(t + 2) * kstep;
;             const char* a3 = a2 + kstep; const char* b3 = b2 + kstep;
;             if (last && has_next) S.a_ready(nxt);
;             if constexpr (SP2) {
;             PG8_LDB(B0, 0, 0); PG8_LDB(B1, 0, 1); PG8_SCHED; PG8_LDA(At, 0, 0); PG8_STAGE(PG8_SA(1, 1), a1 + hstep, voffA);
;             PG8_WAIT_V(8); PG8_WAIT_L(0); PG8_BAR; PG8_MMA(0, 0, At, B0); PG8_MMA(0, 1, At, B1); PG8_BAR; PG8_SCHED;
;             PG8_LDA(At, 0, 1); PG8_STAGE(PG8_SB(0, 0), b2, voffB); PG8_STAGE(PG8_SB(0, 1), b2 + hstep, voffB); PG8_STAGE(PG8_SA(0, 0), a2, voffA);
;             PG8_WAIT_V(8); PG8_WAIT_L(0); PG8_BAR; PG8_MMA(1, 0, At, B0); PG8_MMA(1, 1, At, B1); PG8_BAR; PG8_SCHED;
.LBB0_356:
	s_add_u32 s8, s6, 0xfffc0080
	s_addc_u32 s9, s7, -1
	s_add_i32 s54, 0, 0x10000
	s_cmp_eq_u32 s47, 12
	s_cselect_b32 s11, s29, s9
	s_cselect_b32 s10, s30, s8
	s_cselect_b32 s9, s31, s45
	s_cselect_b32 s8, s34, s35
	s_add_i32 s56, 0, 0x14000
	v_add_u32_e32 v132, s54, v169
	v_add_u32_e32 v180, s56, v169
	ds_read_b128 v[104:107], v132
	ds_read_b128 v[116:119], v132 offset:1024
	ds_read_b128 v[128:131], v132 offset:2048
	ds_read_b128 v[132:135], v132 offset:3072
	ds_read_b128 v[136:139], v180
	ds_read_b128 v[140:143], v180 offset:1024
	ds_read_b128 v[144:147], v180 offset:2048
	ds_read_b128 v[180:183], v180 offset:3072
	v_lshl_add_u64 v[216:217], s[6:7], 0, v[176:177]
	s_add_i32 m0, s15, 0xc000
	ds_read_b128 v[184:187], v239
	ds_read_b128 v[188:191], v239 offset:1024
	ds_read_b128 v[192:195], v239 offset:2048
	ds_read_b128 v[196:199], v239 offset:3072
	ds_read_b128 v[200:203], v239 offset:4096
	ds_read_b128 v[204:207], v239 offset:5120
	ds_read_b128 v[208:211], v239 offset:6144
	ds_read_b128 v[212:215], v239 offset:7168
	global_load_lds_dwordx4 v[216:217], off
	v_lshl_add_u64 v[216:217], s[6:7], 0, v[178:179]
	s_add_i32 m0, s15, 0xe000
	s_nop 0
	global_load_lds_dwordx4 v[216:217], off
	s_waitcnt vmcnt(8)
	s_waitcnt lgkmcnt(0)
	s_barrier
	v_mfma_f32_16x16x32_bf16 v[152:155], v[104:107], v[184:187], v[152:155]
	v_mfma_f32_16x16x32_bf16 v[148:151], v[128:131], v[184:187], v[148:151]
	v_mfma_f32_16x16x32_bf16 v[112:115], v[104:107], v[192:195], v[112:115]
	v_mfma_f32_16x16x32_bf16 v[108:111], v[128:131], v[192:195], v[108:111]
	v_mfma_f32_16x16x32_bf16 v[92:95], v[104:107], v[200:203], v[92:95]
	v_mfma_f32_16x16x32_bf16 v[88:91], v[128:131], v[200:203], v[88:91]
	v_mfma_f32_16x16x32_bf16 v[76:79], v[104:107], v[208:211], v[76:79]
	v_mfma_f32_16x16x32_bf16 v[72:75], v[128:131], v[208:211], v[72:75]
	v_mfma_f32_16x16x32_bf16 v[152:155], v[116:119], v[188:191], v[152:155]
	v_mfma_f32_16x16x32_bf16 v[148:151], v[132:135], v[188:191], v[148:151]
	v_mfma_f32_16x16x32_bf16 v[112:115], v[116:119], v[196:199], v[112:115]
	v_mfma_f32_16x16x32_bf16 v[108:111], v[132:135], v[196:199], v[108:111]
	v_mfma_f32_16x16x32_bf16 v[92:95], v[116:119], v[204:207], v[92:95]
	v_mfma_f32_16x16x32_bf16 v[88:91], v[132:135], v[204:207], v[88:91]
	v_mfma_f32_16x16x32_bf16 v[76:79], v[116:119], v[212:215], v[76:79]
	v_mfma_f32_16x16x32_bf16 v[72:75], v[132:135], v[212:215], v[72:75]
	v_mfma_f32_16x16x32_bf16 v[124:127], v[136:139], v[184:187], v[124:127]
	v_mfma_f32_16x16x32_bf16 v[120:123], v[144:147], v[184:187], v[120:123]
	v_mfma_f32_16x16x32_bf16 v[100:103], v[136:139], v[192:195], v[100:103]
	v_mfma_f32_16x16x32_bf16 v[96:99], v[144:147], v[192:195], v[96:99]
	v_mfma_f32_16x16x32_bf16 v[84:87], v[136:139], v[200:203], v[84:87]
	v_mfma_f32_16x16x32_bf16 v[80:83], v[144:147], v[200:203], v[80:83]
	v_mfma_f32_16x16x32_bf16 v[68:71], v[136:139], v[208:211], v[68:71]
	v_mfma_f32_16x16x32_bf16 v[64:67], v[144:147], v[208:211], v[64:67]
	v_mfma_f32_16x16x32_bf16 v[124:127], v[140:143], v[188:191], v[124:127]
	v_mfma_f32_16x16x32_bf16 v[120:123], v[180:183], v[188:191], v[120:123]
	v_mfma_f32_16x16x32_bf16 v[100:103], v[140:143], v[196:199], v[100:103]
	v_mfma_f32_16x16x32_bf16 v[96:99], v[180:183], v[196:199], v[96:99]
	v_mfma_f32_16x16x32_bf16 v[84:87], v[140:143], v[204:207], v[84:87]
	v_mfma_f32_16x16x32_bf16 v[80:83], v[180:183], v[204:207], v[80:83]
	v_mfma_f32_16x16x32_bf16 v[68:71], v[140:143], v[212:215], v[68:71]
	v_mfma_f32_16x16x32_bf16 v[64:67], v[180:183], v[212:215], v[64:67]
	s_barrier
	s_add_i32 s54, s54, s14
	v_lshl_add_u64 v[216:217], s[8:9], 0, v[156:157]
	s_mov_b32 m0, s54
	ds_read_b128 v[184:187], v239 offset:16384
	ds_read_b128 v[188:191], v239 offset:17408
	ds_read_b128 v[192:195], v239 offset:18432
	ds_read_b128 v[196:199], v239 offset:19456
	ds_read_b128 v[200:203], v239 offset:20480
	ds_read_b128 v[204:207], v239 offset:21504
	ds_read_b128 v[208:211], v239 offset:22528
	ds_read_b128 v[212:215], v239 offset:23552
	global_load_lds_dwordx4 v[216:217], off
	s_add_i32 m0, s54, 0x2000
	s_add_u32 s54, s8, 0x40000
	v_lshl_add_u64 v[218:219], s[8:9], 0, v[170:171]
	s_addc_u32 s55, s9, 0
	s_add_i32 s56, s56, s14
	global_load_lds_dwordx4 v[218:219], off
	v_lshl_add_u64 v[220:221], s[54:55], 0, v[156:157]
	s_mov_b32 m0, s56
	v_lshl_add_u64 v[222:223], s[10:11], 0, v[172:173]
	global_load_lds_dwordx4 v[220:221], off
	v_lshl_add_u64 v[220:221], s[54:55], 0, v[170:171]
	s_add_i32 m0, s56, 0x2000
	s_nop 0
	global_load_lds_dwordx4 v[220:221], off
	v_lshl_add_u64 v[220:221], s[10:11], 0, v[174:175]
	s_mov_b32 m0, s15
	s_nop 0
	global_load_lds_dwordx4 v[220:221], off
	s_mov_b32 m0, s16
	s_nop 0
	global_load_lds_dwordx4 v[222:223], off
	s_waitcnt vmcnt(8)
	s_waitcnt lgkmcnt(0)
	s_barrier
; #define PG8_STAGE(bufoff, gbase, voff) do { _Pragma("unroll") for (int _i = 0; _i < 2; ++_i) \
;         __builtin_amdgcn_global_load_lds((const unsigned*)((const char*)(gbase) + (voff)[_i]), (PG8_LAS unsigned*)(lds + (bufoff) + ldsw + _i * 8192), 16, 0, 0); } while (0)
; #define PG8_LDA(dst, b, h) do { _Pragma("unroll") for (int m = 0; m < 4; ++m) _Pragma("unroll") for (int k = 0; k < 2; ++k) dst[m][k] = *(const PG8_LAS bf16x8*)(lds + PG8_SA(b, h) + aoff + m * 2048 + k * 1024); } while (0)
; #define PG8_LDB(dst, b, h) do { _Pragma("unroll") for (int n = 0; n < 2; ++n) _Pragma("unroll") for (int k = 0; k < 2; ++k) dst[n][k] = *(const PG8_LAS bf16x8*)(lds + PG8_SB(b, h) + boff + n * 2048 + k * 1024); } while (0)
; #define PG8_MMA(ai, bj, At, Bt) do { __builtin_amdgcn_s_setprio(1); _Pragma("unroll") for (int m = 0; m < 4; ++m) _Pragma("unroll") for (int n = 0; n < 2; ++n) _Pragma("unroll") for (int k = 0; k < 2; ++k) \
;         acc[ai][bj][m][n] = __builtin_amdgcn_mfma_f32_16x16x32_bf16(Bt[n][k], At[m][k], acc[ai][bj][m][n], 0, 0, 0); __builtin_amdgcn_s_setprio(0); } while (0)
; #define PG8_WAIT_V(n) asm volatile("s_waitcnt vmcnt(" #n ")" ::: "memory")
; #define PG8_WAIT_L(n) asm volatile("s_waitcnt lgkmcnt(" #n ")" ::: "memory")
; #define PG8_BAR __builtin_amdgcn_s_barrier()
; #define PG8_SCHED __builtin_amdgcn_sched_barrier(0)
; template <class Epi, class Sched, bool ALIGN_EPI = false, bool SP2 = false>
; __device__ __forceinline__ void gemm_phase(PG8_LAS unsigned char* lds, const Gemm g, const Sched& S, const Epi& E) {
;     ...
;             PG8_WAIT_V(8); PG8_WAIT_L(0); PG8_BAR; PG8_MMA(1, 0, At, B0); PG8_MMA(1, 1, At, B1); PG8_BAR; PG8_SCHED;
;             PG8_LDB(B0, 1, 0); PG8_LDB(B1, 1, 1); PG8_SCHED; PG8_LDA(At, 1, 0); PG8_STAGE(PG8_SA(0, 1), a2 + hstep, voffA);
;             PG8_WAIT_V(8); PG8_WAIT_L(0); PG8_BAR; PG8_MMA(0, 0, At, B0); PG8_MMA(0, 1, At, B1); PG8_BAR; PG8_SCHED;
	v_mfma_f32_16x16x32_bf16 v[60:63], v[104:107], v[184:187], v[60:63]
	v_mfma_f32_16x16x32_bf16 v[56:59], v[128:131], v[184:187], v[56:59]
	v_mfma_f32_16x16x32_bf16 v[44:47], v[104:107], v[192:195], v[44:47]
	v_mfma_f32_16x16x32_bf16 v[40:43], v[128:131], v[192:195], v[40:43]
	v_mfma_f32_16x16x32_bf16 v[28:31], v[104:107], v[200:203], v[28:31]
	v_mfma_f32_16x16x32_bf16 v[24:27], v[128:131], v[200:203], v[24:27]
	v_mfma_f32_16x16x32_bf16 v[12:15], v[104:107], v[208:211], v[12:15]
	v_mfma_f32_16x16x32_bf16 v[8:11], v[128:131], v[208:211], v[8:11]
	v_mfma_f32_16x16x32_bf16 v[60:63], v[116:119], v[188:191], v[60:63]
	v_mfma_f32_16x16x32_bf16 v[56:59], v[132:135], v[188:191], v[56:59]
	v_mfma_f32_16x16x32_bf16 v[44:47], v[116:119], v[196:199], v[44:47]
	v_mfma_f32_16x16x32_bf16 v[40:43], v[132:135], v[196:199], v[40:43]
	v_mfma_f32_16x16x32_bf16 v[28:31], v[116:119], v[204:207], v[28:31]
	v_mfma_f32_16x16x32_bf16 v[24:27], v[132:135], v[204:207], v[24:27]
	v_mfma_f32_16x16x32_bf16 v[12:15], v[116:119], v[212:215], v[12:15]
	v_mfma_f32_16x16x32_bf16 v[8:11], v[132:135], v[212:215], v[8:11]
	v_mfma_f32_16x16x32_bf16 v[52:55], v[136:139], v[184:187], v[52:55]
	v_mfma_f32_16x16x32_bf16 v[48:51], v[144:147], v[184:187], v[48:51]
	v_mfma_f32_16x16x32_bf16 v[36:39], v[136:139], v[192:195], v[36:39]
	v_mfma_f32_16x16x32_bf16 v[32:35], v[144:147], v[192:195], v[32:35]
	v_mfma_f32_16x16x32_bf16 v[20:23], v[136:139], v[200:203], v[20:23]
	v_mfma_f32_16x16x32_bf16 v[16:19], v[144:147], v[200:203], v[16:19]
	v_mfma_f32_16x16x32_bf16 v[4:7], v[136:139], v[208:211], v[4:7]
	v_mfma_f32_16x16x32_bf16 v[0:3], v[144:147], v[208:211], v[0:3]
	v_mfma_f32_16x16x32_bf16 v[52:55], v[140:143], v[188:191], v[52:55]
	v_mfma_f32_16x16x32_bf16 v[48:51], v[180:183], v[188:191], v[48:51]
	v_mfma_f32_16x16x32_bf16 v[36:39], v[140:143], v[196:199], v[36:39]
	v_mfma_f32_16x16x32_bf16 v[32:35], v[180:183], v[196:199], v[32:35]
	v_mfma_f32_16x16x32_bf16 v[20:23], v[140:143], v[204:207], v[20:23]
	v_mfma_f32_16x16x32_bf16 v[16:19], v[180:183], v[204:207], v[16:19]
	v_mfma_f32_16x16x32_bf16 v[4:7], v[140:143], v[212:215], v[4:7]
	v_mfma_f32_16x16x32_bf16 v[0:3], v[180:183], v[212:215], v[0:3]
	s_barrier
	s_add_i32 s54, 0, 0x18000
	s_add_i32 s55, 0, 0x1c000
	v_add_u32_e32 v132, s54, v169
	v_add_u32_e32 v180, s55, v169
	ds_read_b128 v[104:107], v132
	ds_read_b128 v[116:119], v132 offset:1024
	ds_read_b128 v[128:131], v132 offset:2048
	ds_read_b128 v[132:135], v132 offset:3072
	ds_read_b128 v[136:139], v180
	ds_read_b128 v[140:143], v180 offset:1024
	ds_read_b128 v[144:147], v180 offset:2048
	ds_read_b128 v[180:183], v180 offset:3072
	s_add_u32 s10, s10, 0x40000
	s_addc_u32 s11, s11, 0
	s_mov_b32 m0, s17
	v_lshl_add_u64 v[224:225], s[10:11], 0, v[174:175]
	ds_read_b128 v[184:187], v239 offset:32768
	ds_read_b128 v[188:191], v239 offset:33792
	ds_read_b128 v[192:195], v239 offset:34816
	ds_read_b128 v[196:199], v239 offset:35840
	ds_read_b128 v[200:203], v239 offset:36864
	ds_read_b128 v[204:207], v239 offset:37888
	ds_read_b128 v[208:211], v239 offset:38912
	ds_read_b128 v[212:215], v239 offset:39936
	global_load_lds_dwordx4 v[224:225], off
	v_lshl_add_u64 v[224:225], s[10:11], 0, v[172:173]
	s_mov_b32 m0, s18
	s_nop 0
	global_load_lds_dwordx4 v[224:225], off
	s_waitcnt vmcnt(8)
	s_waitcnt lgkmcnt(0)
	s_barrier
	v_mfma_f32_16x16x32_bf16 v[152:155], v[104:107], v[184:187], v[152:155]
	v_mfma_f32_16x16x32_bf16 v[148:151], v[128:131], v[184:187], v[148:151]
	v_mfma_f32_16x16x32_bf16 v[112:115], v[104:107], v[192:195], v[112:115]
	v_mfma_f32_16x16x32_bf16 v[108:111], v[128:131], v[192:195], v[108:111]
	v_mfma_f32_16x16x32_bf16 v[92:95], v[104:107], v[200:203], v[92:95]
	v_mfma_f32_16x16x32_bf16 v[88:91], v[128:131], v[200:203], v[88:91]
	v_mfma_f32_16x16x32_bf16 v[76:79], v[104:107], v[208:211], v[76:79]
	v_mfma_f32_16x16x32_bf16 v[72:75], v[128:131], v[208:211], v[72:75]
	v_mfma_f32_16x16x32_bf16 v[152:155], v[116:119], v[188:191], v[152:155]
	v_mfma_f32_16x16x32_bf16 v[148:151], v[132:135], v[188:191], v[148:151]
	v_mfma_f32_16x16x32_bf16 v[112:115], v[116:119], v[196:199], v[112:115]
	v_mfma_f32_16x16x32_bf16 v[108:111], v[132:135], v[196:199], v[108:111]
	v_mfma_f32_16x16x32_bf16 v[92:95], v[116:119], v[204:207], v[92:95]
	v_mfma_f32_16x16x32_bf16 v[88:91], v[132:135], v[204:207], v[88:91]
	v_mfma_f32_16x16x32_bf16 v[76:79], v[116:119], v[212:215], v[76:79]
	v_mfma_f32_16x16x32_bf16 v[72:75], v[132:135], v[212:215], v[72:75]
	v_mfma_f32_16x16x32_bf16 v[124:127], v[136:139], v[184:187], v[124:127]
	v_mfma_f32_16x16x32_bf16 v[120:123], v[144:147], v[184:187], v[120:123]
	v_mfma_f32_16x16x32_bf16 v[100:103], v[136:139], v[192:195], v[100:103]
	v_mfma_f32_16x16x32_bf16 v[96:99], v[144:147], v[192:195], v[96:99]
	v_mfma_f32_16x16x32_bf16 v[84:87], v[136:139], v[200:203], v[84:87]
	v_mfma_f32_16x16x32_bf16 v[80:83], v[144:147], v[200:203], v[80:83]
	v_mfma_f32_16x16x32_bf16 v[68:71], v[136:139], v[208:211], v[68:71]
	v_mfma_f32_16x16x32_bf16 v[64:67], v[144:147], v[208:211], v[64:67]
	v_mfma_f32_16x16x32_bf16 v[124:127], v[140:143], v[188:191], v[124:127]
	v_mfma_f32_16x16x32_bf16 v[120:123], v[180:183], v[188:191], v[120:123]
	v_mfma_f32_16x16x32_bf16 v[100:103], v[140:143], v[196:199], v[100:103]
	v_mfma_f32_16x16x32_bf16 v[96:99], v[180:183], v[196:199], v[96:99]
	v_mfma_f32_16x16x32_bf16 v[84:87], v[140:143], v[204:207], v[84:87]
	v_mfma_f32_16x16x32_bf16 v[80:83], v[180:183], v[204:207], v[80:83]
	v_mfma_f32_16x16x32_bf16 v[68:71], v[140:143], v[212:215], v[68:71]
	v_mfma_f32_16x16x32_bf16 v[64:67], v[180:183], v[212:215], v[64:67]
	s_barrier
; #define PG8_STAGE(bufoff, gbase, voff) do { _Pragma("unroll") for (int _i = 0; _i < 2; ++_i) \
;         __builtin_amdgcn_global_load_lds((const unsigned*)((const char*)(gbase) + (voff)[_i]), (PG8_LAS unsigned*)(lds + (bufoff) + ldsw + _i * 8192), 16, 0, 0); } while (0)
; #define PG8_LDA(dst, b, h) do { _Pragma("unroll") for (int m = 0; m < 4; ++m) _Pragma("unroll") for (int k = 0; k < 2; ++k) dst[m][k] = *(const PG8_LAS bf16x8*)(lds + PG8_SA(b, h) + aoff + m * 2048 + k * 1024); } while (0)
; #define PG8_MMA(ai, bj, At, Bt) do { __builtin_amdgcn_s_setprio(1); _Pragma("unroll") for (int m = 0; m < 4; ++m) _Pragma("unroll") for (int n = 0; n < 2; ++n) _Pragma("unroll") for (int k = 0; k < 2; ++k) \
;         acc[ai][bj][m][n] = __builtin_amdgcn_mfma_f32_16x16x32_bf16(Bt[n][k], At[m][k], acc[ai][bj][m][n], 0, 0, 0); __builtin_amdgcn_s_setprio(0); } while (0)
; #define PG8_WAIT_V(n) asm volatile("s_waitcnt vmcnt(" #n ")" ::: "memory")
; #define PG8_WAIT_L(n) asm volatile("s_waitcnt lgkmcnt(" #n ")" ::: "memory")
; #define PG8_BAR __builtin_amdgcn_s_barrier()
; #define PG8_SCHED __builtin_amdgcn_sched_barrier(0)
; template <class Epi, class Sched, bool ALIGN_EPI = false, bool SP2 = false>
; __device__ __forceinline__ void gemm_phase(PG8_LAS unsigned char* lds, const Gemm g, const Sched& S, const Epi& E) {
;     ...
;         for (int t = 0; t < nt; t += 2) {
;     ...
;             PG8_LDA(At, 1, 1); PG8_STAGE(PG8_SB(1, 0), b3, voffB); PG8_STAGE(PG8_SB(1, 1), b3 + hstep, voffB); PG8_STAGE(PG8_SA(1, 0), a3, voffA);
;             PG8_WAIT_V(8); PG8_WAIT_L(0); PG8_BAR; PG8_MMA(1, 0, At, B0); PG8_MMA(1, 1, At, B1); PG8_BAR; PG8_SCHED;
;     ...
;         if constexpr (ALIGN_EPI) { if (wr == 0) PG8_BAR; }
	s_add_i32 s10, s54, s14
	v_lshl_add_u64 v[216:217], v[216:217], 0, s[96:97]
	s_mov_b32 m0, s10
	ds_read_b128 v[184:187], v239 offset:49152
	ds_read_b128 v[188:191], v239 offset:50176
	ds_read_b128 v[192:195], v239 offset:51200
	ds_read_b128 v[196:199], v239 offset:52224
	ds_read_b128 v[200:203], v239 offset:53248
	ds_read_b128 v[204:207], v239 offset:54272
	ds_read_b128 v[208:211], v239 offset:55296
	ds_read_b128 v[212:215], v239 offset:56320
	global_load_lds_dwordx4 v[216:217], off
	s_add_i32 m0, s10, 0x2000
	s_add_u32 s8, s8, 0x40080
	v_lshl_add_u64 v[216:217], v[218:219], 0, s[96:97]
	s_addc_u32 s9, s9, 0
	s_add_i32 s10, s55, s14
	global_load_lds_dwordx4 v[216:217], off
	v_lshl_add_u64 v[216:217], s[8:9], 0, v[156:157]
	s_mov_b32 m0, s10
	s_nop 0
	global_load_lds_dwordx4 v[216:217], off
	v_lshl_add_u64 v[216:217], s[8:9], 0, v[170:171]
	s_add_i32 m0, s10, 0x2000
	s_nop 0
	global_load_lds_dwordx4 v[216:217], off
	v_lshl_add_u64 v[216:217], v[220:221], 0, s[96:97]
	s_mov_b32 m0, s19
	s_nop 0
	global_load_lds_dwordx4 v[216:217], off
	v_lshl_add_u64 v[216:217], v[222:223], 0, s[96:97]
	s_mov_b32 m0, s20
	s_nop 0
	global_load_lds_dwordx4 v[216:217], off
	s_waitcnt vmcnt(8)
	s_waitcnt lgkmcnt(0)
	s_barrier
	v_mfma_f32_16x16x32_bf16 v[60:63], v[104:107], v[184:187], v[60:63]
	v_mfma_f32_16x16x32_bf16 v[56:59], v[128:131], v[184:187], v[56:59]
	v_mfma_f32_16x16x32_bf16 v[44:47], v[104:107], v[192:195], v[44:47]
	v_mfma_f32_16x16x32_bf16 v[40:43], v[128:131], v[192:195], v[40:43]
	v_mfma_f32_16x16x32_bf16 v[28:31], v[104:107], v[200:203], v[28:31]
	v_mfma_f32_16x16x32_bf16 v[24:27], v[128:131], v[200:203], v[24:27]
	v_mfma_f32_16x16x32_bf16 v[12:15], v[104:107], v[208:211], v[12:15]
	v_mfma_f32_16x16x32_bf16 v[8:11], v[128:131], v[208:211], v[8:11]
	v_mfma_f32_16x16x32_bf16 v[60:63], v[116:119], v[188:191], v[60:63]
	v_mfma_f32_16x16x32_bf16 v[56:59], v[132:135], v[188:191], v[56:59]
	v_mfma_f32_16x16x32_bf16 v[44:47], v[116:119], v[196:199], v[44:47]
	v_mfma_f32_16x16x32_bf16 v[40:43], v[132:135], v[196:199], v[40:43]
	v_mfma_f32_16x16x32_bf16 v[28:31], v[116:119], v[204:207], v[28:31]
	v_mfma_f32_16x16x32_bf16 v[24:27], v[132:135], v[204:207], v[24:27]
	v_mfma_f32_16x16x32_bf16 v[12:15], v[116:119], v[212:215], v[12:15]
	v_mfma_f32_16x16x32_bf16 v[8:11], v[132:135], v[212:215], v[8:11]
	v_mfma_f32_16x16x32_bf16 v[52:55], v[136:139], v[184:187], v[52:55]
	v_mfma_f32_16x16x32_bf16 v[48:51], v[144:147], v[184:187], v[48:51]
	v_mfma_f32_16x16x32_bf16 v[36:39], v[136:139], v[192:195], v[36:39]
	v_mfma_f32_16x16x32_bf16 v[32:35], v[144:147], v[192:195], v[32:35]
	v_mfma_f32_16x16x32_bf16 v[20:23], v[136:139], v[200:203], v[20:23]
	v_mfma_f32_16x16x32_bf16 v[16:19], v[144:147], v[200:203], v[16:19]
	v_mfma_f32_16x16x32_bf16 v[4:7], v[136:139], v[208:211], v[4:7]
	v_mfma_f32_16x16x32_bf16 v[0:3], v[144:147], v[208:211], v[0:3]
	v_mfma_f32_16x16x32_bf16 v[52:55], v[140:143], v[188:191], v[52:55]
	v_mfma_f32_16x16x32_bf16 v[48:51], v[180:183], v[188:191], v[48:51]
	v_mfma_f32_16x16x32_bf16 v[36:39], v[140:143], v[196:199], v[36:39]
	v_mfma_f32_16x16x32_bf16 v[32:35], v[180:183], v[196:199], v[32:35]
	v_mfma_f32_16x16x32_bf16 v[20:23], v[140:143], v[204:207], v[20:23]
	v_mfma_f32_16x16x32_bf16 v[16:19], v[180:183], v[204:207], v[16:19]
	v_mfma_f32_16x16x32_bf16 v[4:7], v[140:143], v[212:215], v[4:7]
	v_mfma_f32_16x16x32_bf16 v[0:3], v[180:183], v[212:215], v[0:3]
	s_barrier
	s_add_i32 s47, s47, 2
	s_add_u32 s6, s6, 0x100
	s_addc_u32 s7, s7, 0
	s_add_u32 s35, s35, 0x100
	s_addc_u32 s45, s45, 0
	s_cmp_gt_u32 s47, 13
	s_cbranch_scc0 .LBB0_356
	s_and_b64 vcc, exec, s[42:43]
	s_cbranch_vccz .LBB0_359
	s_barrier

; #define PG8_STAGE(bufoff, gbase, voff) do { _Pragma("unroll") for (int _i = 0; _i < 2; ++_i) \
;         __builtin_amdgcn_global_load_lds((const unsigned*)((const char*)(gbase) + (voff)[_i]), (PG8_LAS unsigned*)(lds + (bufoff) + ldsw + _i * 8192), 16, 0, 0); } while (0)
; #define PG8_LDA(dst, b, h) do { _Pragma("unroll") for (int m = 0; m < 4; ++m) _Pragma("unroll") for (int k = 0; k < 2; ++k) dst[m][k] = *(const PG8_LAS bf16x8*)(lds + PG8_SA(b, h) + aoff + m * 2048 + k * 1024); } while (0)
; #define PG8_LDB(dst, b, h) do { _Pragma("unroll") for (int n = 0; n < 2; ++n) _Pragma("unroll") for (int k = 0; k < 2; ++k) dst[n][k] = *(const PG8_LAS bf16x8*)(lds + PG8_SB(b, h) + boff + n * 2048 + k * 1024); } while (0)
; #define PG8_MMA(ai, bj, At, Bt) do { __builtin_amdgcn_s_setprio(1); _Pragma("unroll") for (int m = 0; m < 4; ++m) _Pragma("unroll") for (int n = 0; n < 2; ++n) _Pragma("unroll") for (int k = 0; k < 2; ++k) \
;         acc[ai][bj][m][n] = __builtin_amdgcn_mfma_f32_16x16x32_bf16(Bt[n][k], At[m][k], acc[ai][bj][m][n], 0, 0, 0); __builtin_amdgcn_s_setprio(0); } while (0)
; #define PG8_WAIT_V(n) asm volatile("s_waitcnt vmcnt(" #n ")" ::: "memory")
; #define PG8_BAR __builtin_amdgcn_s_barrier()
; template <class Epi, class Sched, bool ALIGN_EPI = false, bool SP2 = false>
; __device__ __forceinline__ void gemm_phase(PG8_LAS unsigned char* lds, const Gemm g, const Sched& S, const Epi& E) {
;     ...
;         for (int t = 0; t < nt; t += 2) {
;             const bool last = (t == nt - 2);
;             const char* a1 = cA + (size_t)(t + 1) * kstep;
;             const char* a2 = last ? nA : cA + (size_t)(t + 2) * kstep; const char* b2 = last ? nB : cB + (size_t)(t + 2) * kstep;
;             const char* a3 = a2 + kstep; const char* b3 = b2 + kstep;
;             if (last && has_next) S.a_ready(nxt);
;             if constexpr (SP2) {
;             PG8_LDB(B0, 0, 0); PG8_LDB(B1, 0, 1); PG8_SCHED; PG8_LDA(At, 0, 0); PG8_STAGE(PG8_SA(1, 1), a1 + hstep, voffA);
;             PG8_WAIT_V(8); PG8_WAIT_L(0); PG8_BAR; PG8_MMA(0, 0, At, B0); PG8_MMA(0, 1, At, B1); PG8_BAR; PG8_SCHED;
;             PG8_LDA(At, 0, 1); PG8_STAGE(PG8_SB(0, 0), b2, voffB); PG8_STAGE(PG8_SB(0, 1), b2 + hstep, voffB); PG8_STAGE(PG8_SA(0, 0), a2, voffA);
;             PG8_WAIT_V(8); PG8_WAIT_L(0); PG8_BAR; PG8_MMA(1, 0, At, B0); PG8_MMA(1, 1, At, B1); PG8_BAR; PG8_SCHED;
.LBB0_399:
	s_add_u32 s12, s10, 0xfffc0080
	s_addc_u32 s13, s11, -1
	s_add_i32 s51, 0, 0x10000
	s_cmp_eq_u32 s50, 12
	s_cselect_b32 s15, s41, s13
	s_cselect_b32 s14, s46, s12
	v_add_u32_e32 v146, s51, v149
	s_cselect_b32 s13, s9, s49
	s_cselect_b32 s12, s47, s48
	s_add_i32 s54, 0, 0x14000
	ds_read_b128 v[138:141], v146
	ds_read_b128 v[142:145], v146 offset:1024
	ds_read_b128 v[168:171], v146 offset:2048
	ds_read_b128 v[172:175], v146 offset:3072
	v_add_u32_e32 v146, s54, v149
	ds_read_b128 v[176:179], v146
	ds_read_b128 v[180:183], v146 offset:1024
	ds_read_b128 v[184:187], v146 offset:2048
	ds_read_b128 v[188:191], v146 offset:3072
	v_lshl_add_u64 v[146:147], s[10:11], 0, v[134:135]
	s_add_i32 m0, s25, 0xc000
	ds_read_b128 v[192:195], v152
	ds_read_b128 v[196:199], v152 offset:1024
	ds_read_b128 v[200:203], v152 offset:2048
	ds_read_b128 v[204:207], v152 offset:3072
	ds_read_b128 v[208:211], v152 offset:4096
	ds_read_b128 v[212:215], v152 offset:5120
	ds_read_b128 v[216:219], v152 offset:6144
	ds_read_b128 v[220:223], v152 offset:7168
	global_load_lds_dwordx4 v[146:147], off
	v_lshl_add_u64 v[146:147], s[10:11], 0, v[136:137]
	s_add_i32 m0, s25, 0xe000
	s_nop 0
	global_load_lds_dwordx4 v[146:147], off
	s_waitcnt vmcnt(8)
	s_waitcnt lgkmcnt(0)
	s_barrier
	v_mfma_f32_16x16x32_bf16 v[124:127], v[138:141], v[192:195], v[124:127]
	v_mfma_f32_16x16x32_bf16 v[120:123], v[168:171], v[192:195], v[120:123]
	v_mfma_f32_16x16x32_bf16 v[108:111], v[138:141], v[200:203], v[108:111]
	v_mfma_f32_16x16x32_bf16 v[104:107], v[168:171], v[200:203], v[104:107]
	v_mfma_f32_16x16x32_bf16 v[92:95], v[138:141], v[208:211], v[92:95]
	v_mfma_f32_16x16x32_bf16 v[88:91], v[168:171], v[208:211], v[88:91]
	v_mfma_f32_16x16x32_bf16 v[76:79], v[138:141], v[216:219], v[76:79]
	v_mfma_f32_16x16x32_bf16 v[72:75], v[168:171], v[216:219], v[72:75]
	v_mfma_f32_16x16x32_bf16 v[124:127], v[142:145], v[196:199], v[124:127]
	v_mfma_f32_16x16x32_bf16 v[120:123], v[172:175], v[196:199], v[120:123]
	v_mfma_f32_16x16x32_bf16 v[108:111], v[142:145], v[204:207], v[108:111]
	v_mfma_f32_16x16x32_bf16 v[104:107], v[172:175], v[204:207], v[104:107]
	v_mfma_f32_16x16x32_bf16 v[92:95], v[142:145], v[212:215], v[92:95]
	v_mfma_f32_16x16x32_bf16 v[88:91], v[172:175], v[212:215], v[88:91]
	v_mfma_f32_16x16x32_bf16 v[76:79], v[142:145], v[220:223], v[76:79]
	v_mfma_f32_16x16x32_bf16 v[72:75], v[172:175], v[220:223], v[72:75]
	v_mfma_f32_16x16x32_bf16 v[116:119], v[176:179], v[192:195], v[116:119]
	v_mfma_f32_16x16x32_bf16 v[112:115], v[184:187], v[192:195], v[112:115]
	v_mfma_f32_16x16x32_bf16 v[100:103], v[176:179], v[200:203], v[100:103]
	v_mfma_f32_16x16x32_bf16 v[96:99], v[184:187], v[200:203], v[96:99]
	v_mfma_f32_16x16x32_bf16 v[84:87], v[176:179], v[208:211], v[84:87]
	v_mfma_f32_16x16x32_bf16 v[80:83], v[184:187], v[208:211], v[80:83]
	v_mfma_f32_16x16x32_bf16 v[68:71], v[176:179], v[216:219], v[68:71]
	v_mfma_f32_16x16x32_bf16 v[64:67], v[184:187], v[216:219], v[64:67]
	v_mfma_f32_16x16x32_bf16 v[116:119], v[180:183], v[196:199], v[116:119]
	v_mfma_f32_16x16x32_bf16 v[112:115], v[188:191], v[196:199], v[112:115]
	v_mfma_f32_16x16x32_bf16 v[100:103], v[180:183], v[204:207], v[100:103]
	v_mfma_f32_16x16x32_bf16 v[96:99], v[188:191], v[204:207], v[96:99]
	v_mfma_f32_16x16x32_bf16 v[84:87], v[180:183], v[212:215], v[84:87]
	v_mfma_f32_16x16x32_bf16 v[80:83], v[188:191], v[212:215], v[80:83]
	v_mfma_f32_16x16x32_bf16 v[68:71], v[180:183], v[220:223], v[68:71]
	v_mfma_f32_16x16x32_bf16 v[64:67], v[188:191], v[220:223], v[64:67]
	s_barrier
	s_add_i32 s51, s51, s21
	v_lshl_add_u64 v[146:147], s[12:13], 0, v[156:157]
	s_mov_b32 m0, s51
	ds_read_b128 v[192:195], v152 offset:16384
	ds_read_b128 v[196:199], v152 offset:17408
	ds_read_b128 v[200:203], v152 offset:18432
	ds_read_b128 v[204:207], v152 offset:19456
	ds_read_b128 v[208:211], v152 offset:20480
	ds_read_b128 v[212:215], v152 offset:21504
	ds_read_b128 v[216:219], v152 offset:22528
	ds_read_b128 v[220:223], v152 offset:23552
	global_load_lds_dwordx4 v[146:147], off
	s_add_i32 m0, s51, 0x2000
	s_add_u32 s52, s12, 0x40000
	v_lshl_add_u64 v[154:155], s[12:13], 0, v[128:129]
	s_addc_u32 s53, s13, 0
	s_add_i32 s51, s54, s21
	global_load_lds_dwordx4 v[154:155], off
	v_lshl_add_u64 v[224:225], s[52:53], 0, v[156:157]
	s_mov_b32 m0, s51
	v_lshl_add_u64 v[226:227], s[14:15], 0, v[130:131]
	global_load_lds_dwordx4 v[224:225], off
	v_lshl_add_u64 v[224:225], s[52:53], 0, v[128:129]
	s_add_i32 m0, s51, 0x2000
	s_nop 0
	global_load_lds_dwordx4 v[224:225], off
	v_lshl_add_u64 v[224:225], s[14:15], 0, v[132:133]
	s_mov_b32 m0, s25
	s_nop 0
	global_load_lds_dwordx4 v[224:225], off
	s_mov_b32 m0, s26
	s_nop 0
	global_load_lds_dwordx4 v[226:227], off
	s_waitcnt vmcnt(8)
	s_waitcnt lgkmcnt(0)
	s_barrier
; #define PG8_STAGE(bufoff, gbase, voff) do { _Pragma("unroll") for (int _i = 0; _i < 2; ++_i) \
;         __builtin_amdgcn_global_load_lds((const unsigned*)((const char*)(gbase) + (voff)[_i]), (PG8_LAS unsigned*)(lds + (bufoff) + ldsw + _i * 8192), 16, 0, 0); } while (0)
; #define PG8_LDA(dst, b, h) do { _Pragma("unroll") for (int m = 0; m < 4; ++m) _Pragma("unroll") for (int k = 0; k < 2; ++k) dst[m][k] = *(const PG8_LAS bf16x8*)(lds + PG8_SA(b, h) + aoff + m * 2048 + k * 1024); } while (0)
; #define PG8_LDB(dst, b, h) do { _Pragma("unroll") for (int n = 0; n < 2; ++n) _Pragma("unroll") for (int k = 0; k < 2; ++k) dst[n][k] = *(const PG8_LAS bf16x8*)(lds + PG8_SB(b, h) + boff + n * 2048 + k * 1024); } while (0)
; #define PG8_MMA(ai, bj, At, Bt) do { __builtin_amdgcn_s_setprio(1); _Pragma("unroll") for (int m = 0; m < 4; ++m) _Pragma("unroll") for (int n = 0; n < 2; ++n) _Pragma("unroll") for (int k = 0; k < 2; ++k) \
;         acc[ai][bj][m][n] = __builtin_amdgcn_mfma_f32_16x16x32_bf16(Bt[n][k], At[m][k], acc[ai][bj][m][n], 0, 0, 0); __builtin_amdgcn_s_setprio(0); } while (0)
; #define PG8_WAIT_V(n) asm volatile("s_waitcnt vmcnt(" #n ")" ::: "memory")
; #define PG8_WAIT_L(n) asm volatile("s_waitcnt lgkmcnt(" #n ")" ::: "memory")
; #define PG8_BAR __builtin_amdgcn_s_barrier()
; #define PG8_SCHED __builtin_amdgcn_sched_barrier(0)
; template <class Epi, class Sched, bool ALIGN_EPI = false, bool SP2 = false>
; __device__ __forceinline__ void gemm_phase(PG8_LAS unsigned char* lds, const Gemm g, const Sched& S, const Epi& E) {
;     ...
;             PG8_WAIT_V(8); PG8_WAIT_L(0); PG8_BAR; PG8_MMA(1, 0, At, B0); PG8_MMA(1, 1, At, B1); PG8_BAR; PG8_SCHED;
;             PG8_LDB(B0, 1, 0); PG8_LDB(B1, 1, 1); PG8_SCHED; PG8_LDA(At, 1, 0); PG8_STAGE(PG8_SA(0, 1), a2 + hstep, voffA);
;             PG8_WAIT_V(8); PG8_WAIT_L(0); PG8_BAR; PG8_MMA(0, 0, At, B0); PG8_MMA(0, 1, At, B1); PG8_BAR; PG8_SCHED;
	v_mfma_f32_16x16x32_bf16 v[60:63], v[138:141], v[192:195], v[60:63]
	v_mfma_f32_16x16x32_bf16 v[56:59], v[168:171], v[192:195], v[56:59]
	v_mfma_f32_16x16x32_bf16 v[44:47], v[138:141], v[200:203], v[44:47]
	v_mfma_f32_16x16x32_bf16 v[40:43], v[168:171], v[200:203], v[40:43]
	v_mfma_f32_16x16x32_bf16 v[28:31], v[138:141], v[208:211], v[28:31]
	v_mfma_f32_16x16x32_bf16 v[24:27], v[168:171], v[208:211], v[24:27]
	v_mfma_f32_16x16x32_bf16 v[12:15], v[138:141], v[216:219], v[12:15]
	v_mfma_f32_16x16x32_bf16 v[8:11], v[168:171], v[216:219], v[8:11]
	v_mfma_f32_16x16x32_bf16 v[60:63], v[142:145], v[196:199], v[60:63]
	v_mfma_f32_16x16x32_bf16 v[56:59], v[172:175], v[196:199], v[56:59]
	v_mfma_f32_16x16x32_bf16 v[44:47], v[142:145], v[204:207], v[44:47]
	v_mfma_f32_16x16x32_bf16 v[40:43], v[172:175], v[204:207], v[40:43]
	v_mfma_f32_16x16x32_bf16 v[28:31], v[142:145], v[212:215], v[28:31]
	v_mfma_f32_16x16x32_bf16 v[24:27], v[172:175], v[212:215], v[24:27]
	v_mfma_f32_16x16x32_bf16 v[12:15], v[142:145], v[220:223], v[12:15]
	v_mfma_f32_16x16x32_bf16 v[8:11], v[172:175], v[220:223], v[8:11]
	v_mfma_f32_16x16x32_bf16 v[52:55], v[176:179], v[192:195], v[52:55]
	v_mfma_f32_16x16x32_bf16 v[48:51], v[184:187], v[192:195], v[48:51]
	v_mfma_f32_16x16x32_bf16 v[36:39], v[176:179], v[200:203], v[36:39]
	v_mfma_f32_16x16x32_bf16 v[32:35], v[184:187], v[200:203], v[32:35]
	v_mfma_f32_16x16x32_bf16 v[20:23], v[176:179], v[208:211], v[20:23]
	v_mfma_f32_16x16x32_bf16 v[16:19], v[184:187], v[208:211], v[16:19]
	v_mfma_f32_16x16x32_bf16 v[4:7], v[176:179], v[216:219], v[4:7]
	v_mfma_f32_16x16x32_bf16 v[0:3], v[184:187], v[216:219], v[0:3]
	v_mfma_f32_16x16x32_bf16 v[52:55], v[180:183], v[196:199], v[52:55]
	v_mfma_f32_16x16x32_bf16 v[48:51], v[188:191], v[196:199], v[48:51]
	v_mfma_f32_16x16x32_bf16 v[36:39], v[180:183], v[204:207], v[36:39]
	v_mfma_f32_16x16x32_bf16 v[32:35], v[188:191], v[204:207], v[32:35]
	v_mfma_f32_16x16x32_bf16 v[20:23], v[180:183], v[212:215], v[20:23]
	v_mfma_f32_16x16x32_bf16 v[16:19], v[188:191], v[212:215], v[16:19]
	v_mfma_f32_16x16x32_bf16 v[4:7], v[180:183], v[220:223], v[4:7]
	v_mfma_f32_16x16x32_bf16 v[0:3], v[188:191], v[220:223], v[0:3]
	s_barrier
	s_add_i32 s51, 0, 0x18000
	v_add_u32_e32 v153, s51, v149
	s_add_i32 s52, 0, 0x1c000
	ds_read_b128 v[138:141], v153
	ds_read_b128 v[142:145], v153 offset:1024
	ds_read_b128 v[168:171], v153 offset:2048
	ds_read_b128 v[172:175], v153 offset:3072
	v_add_u32_e32 v153, s52, v149
	ds_read_b128 v[176:179], v153
	ds_read_b128 v[180:183], v153 offset:1024
	ds_read_b128 v[184:187], v153 offset:2048
	ds_read_b128 v[188:191], v153 offset:3072
	s_add_u32 s14, s14, 0x40000
	s_addc_u32 s15, s15, 0
	s_mov_b32 m0, s27
	v_lshl_add_u64 v[228:229], s[14:15], 0, v[132:133]
	ds_read_b128 v[192:195], v152 offset:32768
	ds_read_b128 v[196:199], v152 offset:33792
	ds_read_b128 v[200:203], v152 offset:34816
	ds_read_b128 v[204:207], v152 offset:35840
	ds_read_b128 v[208:211], v152 offset:36864
	ds_read_b128 v[212:215], v152 offset:37888
	ds_read_b128 v[216:219], v152 offset:38912
	ds_read_b128 v[220:223], v152 offset:39936
	global_load_lds_dwordx4 v[228:229], off
	v_lshl_add_u64 v[228:229], s[14:15], 0, v[130:131]
	s_mov_b32 m0, s28
	s_nop 0
	global_load_lds_dwordx4 v[228:229], off
	s_waitcnt vmcnt(8)
	s_waitcnt lgkmcnt(0)
	s_barrier
	v_mfma_f32_16x16x32_bf16 v[124:127], v[138:141], v[192:195], v[124:127]
	v_mfma_f32_16x16x32_bf16 v[120:123], v[168:171], v[192:195], v[120:123]
	v_mfma_f32_16x16x32_bf16 v[108:111], v[138:141], v[200:203], v[108:111]
	v_mfma_f32_16x16x32_bf16 v[104:107], v[168:171], v[200:203], v[104:107]
	v_mfma_f32_16x16x32_bf16 v[92:95], v[138:141], v[208:211], v[92:95]
	v_mfma_f32_16x16x32_bf16 v[88:91], v[168:171], v[208:211], v[88:91]
	v_mfma_f32_16x16x32_bf16 v[76:79], v[138:141], v[216:219], v[76:79]
	v_mfma_f32_16x16x32_bf16 v[72:75], v[168:171], v[216:219], v[72:75]
	v_mfma_f32_16x16x32_bf16 v[124:127], v[142:145], v[196:199], v[124:127]
	v_mfma_f32_16x16x32_bf16 v[120:123], v[172:175], v[196:199], v[120:123]
	v_mfma_f32_16x16x32_bf16 v[108:111], v[142:145], v[204:207], v[108:111]
	v_mfma_f32_16x16x32_bf16 v[104:107], v[172:175], v[204:207], v[104:107]
	v_mfma_f32_16x16x32_bf16 v[92:95], v[142:145], v[212:215], v[92:95]
	v_mfma_f32_16x16x32_bf16 v[88:91], v[172:175], v[212:215], v[88:91]
	v_mfma_f32_16x16x32_bf16 v[76:79], v[142:145], v[220:223], v[76:79]
	v_mfma_f32_16x16x32_bf16 v[72:75], v[172:175], v[220:223], v[72:75]
	v_mfma_f32_16x16x32_bf16 v[116:119], v[176:179], v[192:195], v[116:119]
	v_mfma_f32_16x16x32_bf16 v[112:115], v[184:187], v[192:195], v[112:115]
	v_mfma_f32_16x16x32_bf16 v[100:103], v[176:179], v[200:203], v[100:103]
	v_mfma_f32_16x16x32_bf16 v[96:99], v[184:187], v[200:203], v[96:99]
	v_mfma_f32_16x16x32_bf16 v[84:87], v[176:179], v[208:211], v[84:87]
	v_mfma_f32_16x16x32_bf16 v[80:83], v[184:187], v[208:211], v[80:83]
	v_mfma_f32_16x16x32_bf16 v[68:71], v[176:179], v[216:219], v[68:71]
	v_mfma_f32_16x16x32_bf16 v[64:67], v[184:187], v[216:219], v[64:67]
	v_mfma_f32_16x16x32_bf16 v[116:119], v[180:183], v[196:199], v[116:119]
	v_mfma_f32_16x16x32_bf16 v[112:115], v[188:191], v[196:199], v[112:115]
	v_mfma_f32_16x16x32_bf16 v[100:103], v[180:183], v[204:207], v[100:103]
	v_mfma_f32_16x16x32_bf16 v[96:99], v[188:191], v[204:207], v[96:99]
	v_mfma_f32_16x16x32_bf16 v[84:87], v[180:183], v[212:215], v[84:87]
	v_mfma_f32_16x16x32_bf16 v[80:83], v[188:191], v[212:215], v[80:83]
	v_mfma_f32_16x16x32_bf16 v[68:71], v[180:183], v[220:223], v[68:71]
	v_mfma_f32_16x16x32_bf16 v[64:67], v[188:191], v[220:223], v[64:67]
	s_barrier
; #define PG8_STAGE(bufoff, gbase, voff) do { _Pragma("unroll") for (int _i = 0; _i < 2; ++_i) \
;         __builtin_amdgcn_global_load_lds((const unsigned*)((const char*)(gbase) + (voff)[_i]), (PG8_LAS unsigned*)(lds + (bufoff) + ldsw + _i * 8192), 16, 0, 0); } while (0)
; #define PG8_LDA(dst, b, h) do { _Pragma("unroll") for (int m = 0; m < 4; ++m) _Pragma("unroll") for (int k = 0; k < 2; ++k) dst[m][k] = *(const PG8_LAS bf16x8*)(lds + PG8_SA(b, h) + aoff + m * 2048 + k * 1024); } while (0)
; #define PG8_MMA(ai, bj, At, Bt) do { __builtin_amdgcn_s_setprio(1); _Pragma("unroll") for (int m = 0; m < 4; ++m) _Pragma("unroll") for (int n = 0; n < 2; ++n) _Pragma("unroll") for (int k = 0; k < 2; ++k) \
;         acc[ai][bj][m][n] = __builtin_amdgcn_mfma_f32_16x16x32_bf16(Bt[n][k], At[m][k], acc[ai][bj][m][n], 0, 0, 0); __builtin_amdgcn_s_setprio(0); } while (0)
; #define PG8_WAIT_V(n) asm volatile("s_waitcnt vmcnt(" #n ")" ::: "memory")
; #define PG8_WAIT_L(n) asm volatile("s_waitcnt lgkmcnt(" #n ")" ::: "memory")
; #define PG8_BAR __builtin_amdgcn_s_barrier()
; #define PG8_SCHED __builtin_amdgcn_sched_barrier(0)
; template <class Epi, class Sched, bool ALIGN_EPI = false, bool SP2 = false>
; __device__ __forceinline__ void gemm_phase(PG8_LAS unsigned char* lds, const Gemm g, const Sched& S, const Epi& E) {
;     ...
;         for (int t = 0; t < nt; t += 2) {
;     ...
;             PG8_LDA(At, 1, 1); PG8_STAGE(PG8_SB(1, 0), b3, voffB); PG8_STAGE(PG8_SB(1, 1), b3 + hstep, voffB); PG8_STAGE(PG8_SA(1, 0), a3, voffA);
;             PG8_WAIT_V(8); PG8_WAIT_L(0); PG8_BAR; PG8_MMA(1, 0, At, B0); PG8_MMA(1, 1, At, B1); PG8_BAR; PG8_SCHED;
;     ...
;         if constexpr (ALIGN_EPI) { if (wr == 0) PG8_BAR; }
	s_add_i32 s14, s51, s21
	v_lshl_add_u64 v[146:147], v[146:147], 0, s[96:97]
	s_mov_b32 m0, s14
	ds_read_b128 v[192:195], v152 offset:49152
	ds_read_b128 v[196:199], v152 offset:50176
	ds_read_b128 v[200:203], v152 offset:51200
	ds_read_b128 v[204:207], v152 offset:52224
	ds_read_b128 v[208:211], v152 offset:53248
	ds_read_b128 v[212:215], v152 offset:54272
	ds_read_b128 v[216:219], v152 offset:55296
	ds_read_b128 v[220:223], v152 offset:56320
	global_load_lds_dwordx4 v[146:147], off
	s_add_i32 m0, s14, 0x2000
	s_add_u32 s12, s12, 0x40080
	v_lshl_add_u64 v[146:147], v[154:155], 0, s[96:97]
	s_addc_u32 s13, s13, 0
	s_add_i32 s14, s52, s21
	global_load_lds_dwordx4 v[146:147], off
	v_lshl_add_u64 v[146:147], s[12:13], 0, v[156:157]
	s_mov_b32 m0, s14
	s_nop 0
	global_load_lds_dwordx4 v[146:147], off
	v_lshl_add_u64 v[146:147], s[12:13], 0, v[128:129]
	s_add_i32 m0, s14, 0x2000
	s_nop 0
	global_load_lds_dwordx4 v[146:147], off
	v_lshl_add_u64 v[146:147], v[224:225], 0, s[96:97]
	s_mov_b32 m0, s29
	s_nop 0
	global_load_lds_dwordx4 v[146:147], off
	v_lshl_add_u64 v[146:147], v[226:227], 0, s[96:97]
	s_mov_b32 m0, s30
	s_nop 0
	global_load_lds_dwordx4 v[146:147], off
	s_waitcnt vmcnt(8)
	s_waitcnt lgkmcnt(0)
	s_barrier
	v_mfma_f32_16x16x32_bf16 v[60:63], v[138:141], v[192:195], v[60:63]
	v_mfma_f32_16x16x32_bf16 v[56:59], v[168:171], v[192:195], v[56:59]
	v_mfma_f32_16x16x32_bf16 v[44:47], v[138:141], v[200:203], v[44:47]
	v_mfma_f32_16x16x32_bf16 v[40:43], v[168:171], v[200:203], v[40:43]
	v_mfma_f32_16x16x32_bf16 v[28:31], v[138:141], v[208:211], v[28:31]
	v_mfma_f32_16x16x32_bf16 v[24:27], v[168:171], v[208:211], v[24:27]
	v_mfma_f32_16x16x32_bf16 v[12:15], v[138:141], v[216:219], v[12:15]
	v_mfma_f32_16x16x32_bf16 v[8:11], v[168:171], v[216:219], v[8:11]
	v_mfma_f32_16x16x32_bf16 v[60:63], v[142:145], v[196:199], v[60:63]
	v_mfma_f32_16x16x32_bf16 v[56:59], v[172:175], v[196:199], v[56:59]
	v_mfma_f32_16x16x32_bf16 v[44:47], v[142:145], v[204:207], v[44:47]
	v_mfma_f32_16x16x32_bf16 v[40:43], v[172:175], v[204:207], v[40:43]
	v_mfma_f32_16x16x32_bf16 v[28:31], v[142:145], v[212:215], v[28:31]
	v_mfma_f32_16x16x32_bf16 v[24:27], v[172:175], v[212:215], v[24:27]
	v_mfma_f32_16x16x32_bf16 v[12:15], v[142:145], v[220:223], v[12:15]
	v_mfma_f32_16x16x32_bf16 v[8:11], v[172:175], v[220:223], v[8:11]
	v_mfma_f32_16x16x32_bf16 v[52:55], v[176:179], v[192:195], v[52:55]
	v_mfma_f32_16x16x32_bf16 v[48:51], v[184:187], v[192:195], v[48:51]
	v_mfma_f32_16x16x32_bf16 v[36:39], v[176:179], v[200:203], v[36:39]
	v_mfma_f32_16x16x32_bf16 v[32:35], v[184:187], v[200:203], v[32:35]
	v_mfma_f32_16x16x32_bf16 v[20:23], v[176:179], v[208:211], v[20:23]
	v_mfma_f32_16x16x32_bf16 v[16:19], v[184:187], v[208:211], v[16:19]
	v_mfma_f32_16x16x32_bf16 v[4:7], v[176:179], v[216:219], v[4:7]
	v_mfma_f32_16x16x32_bf16 v[0:3], v[184:187], v[216:219], v[0:3]
	v_mfma_f32_16x16x32_bf16 v[52:55], v[180:183], v[196:199], v[52:55]
	v_mfma_f32_16x16x32_bf16 v[48:51], v[188:191], v[196:199], v[48:51]
	v_mfma_f32_16x16x32_bf16 v[36:39], v[180:183], v[204:207], v[36:39]
	v_mfma_f32_16x16x32_bf16 v[32:35], v[188:191], v[204:207], v[32:35]
	v_mfma_f32_16x16x32_bf16 v[20:23], v[180:183], v[212:215], v[20:23]
	v_mfma_f32_16x16x32_bf16 v[16:19], v[188:191], v[212:215], v[16:19]
	v_mfma_f32_16x16x32_bf16 v[4:7], v[180:183], v[220:223], v[4:7]
	v_mfma_f32_16x16x32_bf16 v[0:3], v[188:191], v[220:223], v[0:3]
	s_barrier
	s_add_i32 s50, s50, 2
	s_add_u32 s10, s10, 0x100
	s_addc_u32 s11, s11, 0
	s_add_u32 s48, s48, 0x100
	s_addc_u32 s49, s49, 0
	s_cmp_gt_u32 s50, 13
	s_cbranch_scc0 .LBB0_399
	s_and_b64 vcc, exec, s[6:7]
	s_cbranch_vccz .LBB0_402
	s_barrier
